# attn_d: row-sum trigger (exp first, max tree only in the rare path), p held in registers borrowed from hoisted constants
# baseline (speedup 1.0000x reference)
.LBB0_610:
	s_ashr_i32 s5, s23, 7
	s_bfe_u32 s4, s23, 0x20005
	s_mul_hi_i32 s8, s5, 0x3e00000
	s_mul_i32 s5, s5, 0x3e00000
	s_add_u32 s18, s2, s5
	s_addc_u32 s19, s17, s8
	s_lshl_b32 s5, s23, 7
	s_and_b32 s5, s5, 0xf80
	v_and_b32_e32 v64, 15, v2
	v_lshl_add_u32 v0, v3, 4, s5
	v_or_b32_e32 v66, v0, v64
	v_mov_b64_e32 v[20:21], s[18:19]
	v_mad_i64_i32 v[4:5], s[18:19], v66, s65, v[20:21]
	s_lshl_b32 s8, s4, 8
	v_bfe_u32 v65, v2, 4, 2
	v_lshl_add_u64 v[4:5], v[4:5], 0, s[8:9]
	s_mov_b64 s[18:19], 0x2200
	v_lshl_add_u64 v[132:133], v[4:5], 0, s[18:19]
	v_lshlrev_b32_e32 v0, 4, v65
	v_lshl_add_u64 v[16:17], v[132:133], 0, v[0:1]
	v_ashrrev_i32_e32 v67, 4, v2
	global_load_dwordx4 v[4:7], v[16:17], off
	global_load_dwordx4 v[8:11], v[16:17], off offset:64
	global_load_dwordx4 v[12:15], v[16:17], off offset:128
	s_nop 0
	global_load_dwordx4 v[16:19], v[16:17], off offset:192
	v_lshlrev_b32_e32 v0, 4, v2
	v_mad_i64_i32 v[20:21], s[18:19], v67, s65, v[20:21]
	v_lshl_add_u64 v[20:21], v[20:21], 0, s[8:9]
	v_and_b32_e32 v0, 0xf0, v0
	v_lshl_add_u64 v[36:37], v[20:21], 0, v[0:1]
	v_add_co_u32_e32 v24, vcc, s64, v36
	s_mov_b32 s5, 0x7e000
	s_nop 0
	v_addc_co_u32_e32 v25, vcc, 0, v37, vcc
	v_add_co_u32_e32 v32, vcc, s5, v36
	s_mov_b64 s[18:19], 0x2600
	s_waitcnt lgkmcnt(0)
	v_addc_co_u32_e32 v33, vcc, 0, v37, vcc
	global_load_dwordx4 v[20:23], v[24:25], off offset:1536
	s_nop 0
	global_load_dwordx4 v[24:27], v[24:25], off offset:2560
	s_nop 0
	global_load_dwordx4 v[28:31], v[32:33], off offset:1536
	s_nop 0
	global_load_dwordx4 v[32:35], v[32:33], off offset:2560
	v_lshl_add_u64 v[134:135], v[36:37], 0, s[18:19]
	s_mov_b64 s[18:19], 0x2a00
	v_lshl_add_u64 v[136:137], v[36:37], 0, s[18:19]
	v_mul_lo_u32 v36, v67, s21
	v_add3_u32 v169, 0, v0, v36
	v_lshlrev_b32_e32 v167, 2, v65
	s_barrier
	s_not_b32 s4, s4
	s_lshl_b32 s4, s4, 1
	v_ldexp_f32 v0, 1.0, s4
	v_lshlrev_b32_e32 v68, 3, v65
	v_mul_f32_e32 v150, 0x3fb8aa3b, v0
	v_readfirstlane_b32 s4, v3
	v_mul_u32_u24_e32 v0, 0x90, v64
	s_cmp_gt_i32 s4, 3
	s_mov_b64 s[4:5], -1
	v_lshlrev_b32_e32 v171, 1, v0
	v_lshlrev_b32_e32 v172, 1, v68
	s_waitcnt vmcnt(3)
	ds_write_b128 v169, v[20:23]
	s_waitcnt vmcnt(2)
	ds_write_b128 v169, v[24:27] offset:36864
	s_waitcnt vmcnt(1)
	ds_write_b128 v169, v[28:31] offset:9216
	s_waitcnt vmcnt(0)
	ds_write_b128 v169, v[32:35] offset:46080
	v_lshlrev_b32_e32 v38, 16, v4
	v_and_b32_e32 v39, 0xffff0000, v4
	v_lshlrev_b32_e32 v4, 16, v5
	v_and_b32_e32 v5, 0xffff0000, v5
	v_lshlrev_b32_e32 v50, 16, v16
	v_and_b32_e32 v51, 0xffff0000, v16
	v_pk_mul_f32 v[38:39], v[38:39], s[16:17] op_sel_hi:[1,0]
	v_pk_mul_f32 v[52:53], v[4:5], s[16:17] op_sel_hi:[1,0]
	v_cvt_pk_bf16_f32 v4, v38, v39
	v_pk_mul_f32 v[38:39], v[50:51], s[16:17] op_sel_hi:[1,0]
	v_sub_u32_e32 v20, v167, v66
	v_cvt_pk_bf16_f32 v16, v38, v39
	v_lshlrev_b32_e32 v38, 16, v17
	v_and_b32_e32 v39, 0xffff0000, v17
	v_pk_mul_f32 v[38:39], v[38:39], s[16:17] op_sel_hi:[1,0]
	v_cvt_f32_i32_e32 v170, v20
	v_cvt_pk_bf16_f32 v17, v38, v39
	v_lshlrev_b32_e32 v38, 16, v18
	v_and_b32_e32 v39, 0xffff0000, v18
	v_pk_mul_f32 v[38:39], v[38:39], s[16:17] op_sel_hi:[1,0]
	v_lshlrev_b32_e32 v40, 16, v6
	v_cvt_pk_bf16_f32 v18, v38, v39
	v_lshlrev_b32_e32 v38, 16, v19
	v_and_b32_e32 v39, 0xffff0000, v19
	v_pk_mul_f32 v[38:39], v[38:39], s[16:17] op_sel_hi:[1,0]
	v_and_b32_e32 v41, 0xffff0000, v6
	v_cvt_pk_bf16_f32 v19, v38, v39
	v_lshlrev_b32_e32 v38, 3, v2
	v_bfe_u32 v2, v2, 2, 2
	v_lshlrev_b32_e32 v6, 16, v7
	v_and_b32_e32 v7, 0xffff0000, v7
	v_lshlrev_b32_e32 v42, 16, v8
	v_and_b32_e32 v43, 0xffff0000, v8
	v_lshlrev_b32_e32 v8, 16, v9
	v_and_b32_e32 v9, 0xffff0000, v9
	v_lshlrev_b32_e32 v44, 16, v10
	v_and_b32_e32 v45, 0xffff0000, v10
	v_lshlrev_b32_e32 v10, 16, v11
	v_and_b32_e32 v11, 0xffff0000, v11
	v_lshlrev_b32_e32 v46, 16, v12
	v_and_b32_e32 v47, 0xffff0000, v12
	v_lshlrev_b32_e32 v12, 16, v13
	v_and_b32_e32 v13, 0xffff0000, v13
	v_lshlrev_b32_e32 v48, 16, v14
	v_and_b32_e32 v49, 0xffff0000, v14
	v_lshlrev_b32_e32 v14, 16, v15
	v_and_b32_e32 v15, 0xffff0000, v15
	v_or_b32_e32 v2, v167, v2
	v_pk_mul_f32 v[40:41], v[40:41], s[16:17] op_sel_hi:[1,0]
	v_pk_mul_f32 v[54:55], v[6:7], s[16:17] op_sel_hi:[1,0]
	v_pk_mul_f32 v[42:43], v[42:43], s[16:17] op_sel_hi:[1,0]
	v_pk_mul_f32 v[56:57], v[8:9], s[16:17] op_sel_hi:[1,0]
	v_pk_mul_f32 v[44:45], v[44:45], s[16:17] op_sel_hi:[1,0]
	v_pk_mul_f32 v[58:59], v[10:11], s[16:17] op_sel_hi:[1,0]
	v_pk_mul_f32 v[46:47], v[46:47], s[16:17] op_sel_hi:[1,0]
	v_pk_mul_f32 v[60:61], v[12:13], s[16:17] op_sel_hi:[1,0]
	v_pk_mul_f32 v[48:49], v[48:49], s[16:17] op_sel_hi:[1,0]
	v_pk_mul_f32 v[62:63], v[14:15], s[16:17] op_sel_hi:[1,0]
	v_and_b32_e32 v3, 24, v38
	v_mad_u32_u24 v2, v2, s21, 0
	v_cvt_pk_bf16_f32 v5, v52, v53
	v_cvt_pk_bf16_f32 v6, v40, v41
	v_cvt_pk_bf16_f32 v7, v54, v55
	v_cvt_pk_bf16_f32 v8, v42, v43
	v_cvt_pk_bf16_f32 v9, v56, v57
	v_cvt_pk_bf16_f32 v10, v44, v45
	v_cvt_pk_bf16_f32 v11, v58, v59
	v_cvt_pk_bf16_f32 v12, v46, v47
	v_cvt_pk_bf16_f32 v13, v60, v61
	v_cvt_pk_bf16_f32 v14, v48, v49
	v_cvt_pk_bf16_f32 v15, v62, v63
	v_add_u32_e32 v168, v2, v3
	s_waitcnt lgkmcnt(0)
	s_barrier
	s_cbranch_scc0 .Ld_groupA
	v_mov_b32_e32 v28, 0
	v_mov_b32_e32 v29, 0
	v_mov_b32_e32 v30, 0
	v_mov_b32_e32 v31, 0
	v_mov_b32_e32 v32, 0
	v_mov_b32_e32 v33, 0
	v_mov_b32_e32 v34, 0
	v_mov_b32_e32 v35, 0
	v_mov_b32_e32 v40, 0
	v_mov_b32_e32 v41, 0
	v_mov_b32_e32 v42, 0
	v_mov_b32_e32 v43, 0
	v_mov_b32_e32 v52, 0
	v_mov_b32_e32 v53, 0
	v_mov_b32_e32 v54, 0
	v_mov_b32_e32 v55, 0
	v_mov_b32_e32 v56, 0
	v_mov_b32_e32 v57, 0
	v_mov_b32_e32 v58, 0
	v_mov_b32_e32 v59, 0
	v_mov_b32_e32 v64, 0
	v_mov_b32_e32 v65, 0
	v_mov_b32_e32 v66, 0
	v_mov_b32_e32 v67, 0
	v_mov_b32_e32 v72, 0
	v_mov_b32_e32 v73, 0
	v_mov_b32_e32 v74, 0
	v_mov_b32_e32 v75, 0
	v_mov_b32_e32 v84, 0
	v_mov_b32_e32 v85, 0
	v_mov_b32_e32 v86, 0
	v_mov_b32_e32 v87, 0
	v_mov_b32_e32 v36, 0
	v_mov_b32_e32 v37, 0
	v_mov_b32_e32 v38, 0
	v_mov_b32_e32 v39, 0
	v_mov_b32_e32 v44, 0
	v_mov_b32_e32 v45, 0
	v_mov_b32_e32 v46, 0
	v_mov_b32_e32 v47, 0
	v_mov_b32_e32 v48, 0
	v_mov_b32_e32 v49, 0
	v_mov_b32_e32 v50, 0
	v_mov_b32_e32 v51, 0
	v_mov_b32_e32 v60, 0
	v_mov_b32_e32 v61, 0
	v_mov_b32_e32 v62, 0
	v_mov_b32_e32 v63, 0
	v_mov_b32_e32 v68, 0
	v_mov_b32_e32 v69, 0
	v_mov_b32_e32 v70, 0
	v_mov_b32_e32 v71, 0
	v_mov_b32_e32 v76, 0
	v_mov_b32_e32 v77, 0
	v_mov_b32_e32 v78, 0
	v_mov_b32_e32 v79, 0
	v_mov_b32_e32 v80, 0
	v_mov_b32_e32 v81, 0
	v_mov_b32_e32 v82, 0
	v_mov_b32_e32 v83, 0
	v_mov_b32_e32 v20, 0
	v_mov_b32_e32 v21, 0
	v_mov_b32_e32 v22, 0
	v_mov_b32_e32 v23, 0
	v_mov_b32_e32 v120, 0
	v_mov_b32_e32 v121, 0
	v_mov_b32_e32 v122, 0
	v_mov_b32_e32 v123, 0
	v_mov_b32_e32 v124, 0
	v_mov_b32_e32 v125, 0
	v_mov_b32_e32 v126, 0
	v_mov_b32_e32 v127, 0
	v_mov_b32_e32 v128, 0
	v_mov_b32_e32 v129, 0
	v_mov_b32_e32 v130, 0
	v_mov_b32_e32 v131, 0
	v_mov_b32_e32 v152, 0
	v_mov_b32_e32 v153, 0
	v_mov_b32_e32 v154, 0
	v_mov_b32_e32 v155, 0
	v_mov_b32_e32 v0, 0
	v_mov_b32_e32 v151, 0
	v_mov_b32_e32 v24, 0
	v_mov_b32_e32 v25, 0
	s_mov_b32 s66, 0xff800000
	s_mov_b32 s67, 0xff800000
	v_add_u32_e32 v255, v171, v172
	v_mov_b32_e32 v165, v170
	v_readfirstlane_b32 s42, v134
	v_readfirstlane_b32 s43, v135
	v_readfirstlane_b32 s46, v136
	v_readfirstlane_b32 s47, v137
	s_nop 3
	v_subrev_u32_e32 v173, s42, v134
	v_subrev_u32_e32 v175, s46, v136
	s_mov_b32 s5, 0
	s_mov_b32 s31, 0
	s_mov_b32 s38, 0
	s_mov_b32 s39, 0x4800
	s_mov_b32 s30, 0xf8000
	v_add_u32_e32 v174, s31, v168
	v_add_u32_e32 v164, s39, v169
	s_add_u32 s80, s42, s30
	s_addc_u32 s81, s43, 0
	s_add_u32 s86, s80, 0x7c000
	s_addc_u32 s87, s81, 0
	s_add_u32 s96, s46, s30
	s_addc_u32 s97, s47, 0
	s_add_u32 s98, s96, 0x7c000
	s_addc_u32 s99, s97, 0
	v_mov_b32_e32 v88, 0xff800000
	v_mov_b32_e32 v89, 0xff800000
	v_mov_b32_e32 v90, 0xff800000
	v_mov_b32_e32 v91, 0xff800000
	v_mov_b32_e32 v92, 0xff800000
	v_mov_b32_e32 v93, 0xff800000
	v_mov_b32_e32 v94, 0xff800000
	v_mov_b32_e32 v95, 0xff800000
	v_mov_b32_e32 v96, 0xff800000
	v_mov_b32_e32 v97, 0xff800000
	v_mov_b32_e32 v98, 0xff800000
	v_mov_b32_e32 v99, 0xff800000
	v_mov_b32_e32 v100, 0xff800000
	v_mov_b32_e32 v101, 0xff800000
	v_mov_b32_e32 v102, 0xff800000
	v_mov_b32_e32 v103, 0xff800000
	v_mov_b32_e32 v104, 0xff800000
	v_mov_b32_e32 v105, 0xff800000
	v_mov_b32_e32 v106, 0xff800000
	v_mov_b32_e32 v107, 0xff800000
	v_mov_b32_e32 v108, 0xff800000
	v_mov_b32_e32 v109, 0xff800000
	v_mov_b32_e32 v110, 0xff800000
	v_mov_b32_e32 v111, 0xff800000
	v_mov_b32_e32 v112, 0xff800000
	v_mov_b32_e32 v113, 0xff800000
	v_mov_b32_e32 v114, 0xff800000
	v_mov_b32_e32 v115, 0xff800000
	v_mov_b32_e32 v116, 0xff800000
	v_mov_b32_e32 v117, 0xff800000
	v_mov_b32_e32 v118, 0xff800000
	v_mov_b32_e32 v119, 0xff800000
.Ld_loopB:
	global_load_dwordx4 v[212:215], v173, s[80:81]
	global_load_dwordx4 v[220:223], v175, s[96:97]
	global_load_dwordx4 v[216:219], v173, s[86:87]
	global_load_dwordx4 v[224:227], v175, s[98:99]
	ds_read_b128 v[228:231], v255 offset:0
	ds_read_b128 v[232:235], v255 offset:64
	ds_read_b128 v[236:239], v255 offset:4608
	ds_read_b128 v[240:243], v255 offset:4672
	v_exp_f32_e32 v138, v88
	v_exp_f32_e32 v139, v89
	v_exp_f32_e32 v140, v90
	v_exp_f32_e32 v141, v91
	v_exp_f32_e32 v142, v92
	v_exp_f32_e32 v143, v93
	v_exp_f32_e32 v144, v94
	v_exp_f32_e32 v145, v95
	v_exp_f32_e32 v146, v96
	v_exp_f32_e32 v147, v97
	v_exp_f32_e32 v148, v98
	v_exp_f32_e32 v149, v99
	v_exp_f32_e32 v194, v100
	v_exp_f32_e32 v195, v101
	v_exp_f32_e32 v196, v102
	v_exp_f32_e32 v197, v103
	s_nop 0
	v_add_f32_e32 v26, v138, v139
	v_add_f32_e32 v26, v26, v140
	v_add_f32_e32 v26, v26, v141
	v_add_f32_e32 v26, v26, v142
	v_add_f32_e32 v26, v26, v143
	v_add_f32_e32 v26, v26, v144
	v_add_f32_e32 v26, v26, v145
	v_add_f32_e32 v26, v26, v146
	v_add_f32_e32 v26, v26, v147
	v_add_f32_e32 v26, v26, v148
	v_add_f32_e32 v26, v26, v149
	v_add_f32_e32 v26, v26, v194
	v_add_f32_e32 v26, v26, v195
	v_add_f32_e32 v26, v26, v196
	v_add_f32_e32 v26, v26, v197
	v_cmp_lt_f32_e32 vcc, s66, v26
	s_cbranch_vccnz .Ld_rare_B0_0
.Ld_back_B0_0:
	v_add_f32_e32 v0, v0, v26
	v_cvt_pk_bf16_f32 v120, v138, v139
	v_cvt_pk_bf16_f32 v121, v140, v141
	v_cvt_pk_bf16_f32 v122, v142, v143
	v_cvt_pk_bf16_f32 v123, v144, v145
	v_cvt_pk_bf16_f32 v124, v146, v147
	v_cvt_pk_bf16_f32 v125, v148, v149
	v_cvt_pk_bf16_f32 v126, v194, v195
	v_cvt_pk_bf16_f32 v127, v196, v197
	v_exp_f32_e32 v138, v104
	v_exp_f32_e32 v139, v105
	v_exp_f32_e32 v140, v106
	v_exp_f32_e32 v141, v107
	v_exp_f32_e32 v142, v108
	v_exp_f32_e32 v143, v109
	v_exp_f32_e32 v144, v110
	v_exp_f32_e32 v145, v111
	v_exp_f32_e32 v146, v112
	v_exp_f32_e32 v147, v113
	v_exp_f32_e32 v148, v114
	v_exp_f32_e32 v149, v115
	v_exp_f32_e32 v194, v116
	v_exp_f32_e32 v195, v117
	v_exp_f32_e32 v196, v118
	v_exp_f32_e32 v197, v119
	s_nop 0
	v_add_f32_e32 v26, v138, v139
	v_add_f32_e32 v26, v26, v140
	v_add_f32_e32 v26, v26, v141
	v_add_f32_e32 v26, v26, v142
	v_add_f32_e32 v26, v26, v143
	v_add_f32_e32 v26, v26, v144
	v_add_f32_e32 v26, v26, v145
	v_add_f32_e32 v26, v26, v146
	v_add_f32_e32 v26, v26, v147
	v_add_f32_e32 v26, v26, v148
	v_add_f32_e32 v26, v26, v149
	v_add_f32_e32 v26, v26, v194
	v_add_f32_e32 v26, v26, v195
	v_add_f32_e32 v26, v26, v196
	v_add_f32_e32 v26, v26, v197
	v_cmp_lt_f32_e32 vcc, s66, v26
	s_cbranch_vccnz .Ld_rare_B0_1
.Ld_back_B0_1:
	v_add_f32_e32 v151, v151, v26
	v_cvt_pk_bf16_f32 v128, v138, v139
	v_cvt_pk_bf16_f32 v129, v140, v141
	v_cvt_pk_bf16_f32 v130, v142, v143
	v_cvt_pk_bf16_f32 v131, v144, v145
	v_cvt_pk_bf16_f32 v152, v146, v147
	v_cvt_pk_bf16_f32 v153, v148, v149
	v_cvt_pk_bf16_f32 v154, v194, v195
	v_cvt_pk_bf16_f32 v155, v196, v197
	v_mov_b32_e32 v156, v165
	v_add_f32_e32 v157, 0x3f800000, v165
	v_add_f32_e32 v158, 0x40000000, v165
	v_add_f32_e32 v159, 0x40400000, v165
	v_add_f32_e32 v160, 0x41800000, v165
	v_add_f32_e32 v161, 0x41880000, v165
	v_add_f32_e32 v162, 0x41900000, v165
	v_add_f32_e32 v163, 0x41980000, v165
	v_add_f32_e32 v176, 0x42000000, v165
	v_add_f32_e32 v177, 0x42040000, v165
	v_add_f32_e32 v178, 0x42080000, v165
	v_add_f32_e32 v179, 0x420c0000, v165
	v_add_f32_e32 v180, 0x42400000, v165
	v_add_f32_e32 v181, 0x42440000, v165
	v_add_f32_e32 v182, 0x42480000, v165
	v_add_f32_e32 v183, 0x424c0000, v165
	v_fma_f32 v204, -v150, |v156|, v25
	v_fma_f32 v205, -v150, |v157|, v25
	v_fma_f32 v206, -v150, |v158|, v25
	v_fma_f32 v207, -v150, |v159|, v25
	v_fma_f32 v208, -v150, |v160|, v25
	v_fma_f32 v209, -v150, |v161|, v25
	v_fma_f32 v210, -v150, |v162|, v25
	v_fma_f32 v211, -v150, |v163|, v25
	v_fma_f32 v184, -v150, |v176|, v25
	v_fma_f32 v185, -v150, |v177|, v25
	v_fma_f32 v186, -v150, |v178|, v25
	v_fma_f32 v187, -v150, |v179|, v25
	v_fma_f32 v188, -v150, |v180|, v25
	v_fma_f32 v189, -v150, |v181|, v25
	v_fma_f32 v190, -v150, |v182|, v25
	v_fma_f32 v191, -v150, |v183|, v25
	v_fma_f32 v156, -v150, |v156|, v24
	v_fma_f32 v157, -v150, |v157|, v24
	v_fma_f32 v158, -v150, |v158|, v24
	v_fma_f32 v159, -v150, |v159|, v24
	v_fma_f32 v160, -v150, |v160|, v24
	v_fma_f32 v161, -v150, |v161|, v24
	v_fma_f32 v162, -v150, |v162|, v24
	v_fma_f32 v163, -v150, |v163|, v24
	v_fma_f32 v176, -v150, |v176|, v24
	v_fma_f32 v177, -v150, |v177|, v24
	v_fma_f32 v178, -v150, |v178|, v24
	v_fma_f32 v179, -v150, |v179|, v24
	v_fma_f32 v180, -v150, |v180|, v24
	v_fma_f32 v181, -v150, |v181|, v24
	v_fma_f32 v182, -v150, |v182|, v24
	v_fma_f32 v183, -v150, |v183|, v24
	ds_read_b128 v[244:247], v255 offset:9216
	s_waitcnt lgkmcnt(4)
	v_mfma_f32_16x16x32_bf16 v[88:91], v[228:231], v[4:7], v[156:159]
	ds_read_b128 v[248:251], v255 offset:9280
	s_waitcnt lgkmcnt(4)
	v_mfma_f32_16x16x32_bf16 v[88:91], v[232:235], v[8:11], v[88:91]
	ds_read_b128 v[228:231], v255 offset:13824
	s_waitcnt lgkmcnt(4)
	v_mfma_f32_16x16x32_bf16 v[92:95], v[236:239], v[4:7], v[160:163]
	ds_read_b128 v[232:235], v255 offset:13888
	s_waitcnt lgkmcnt(4)
	v_mfma_f32_16x16x32_bf16 v[92:95], v[240:243], v[8:11], v[92:95]
	ds_read_b128 v[236:239], v255 offset:128
	s_waitcnt lgkmcnt(4)
	v_mfma_f32_16x16x32_bf16 v[96:99], v[244:247], v[4:7], v[176:179]
	ds_read_b128 v[240:243], v255 offset:192
	s_waitcnt lgkmcnt(4)
	v_mfma_f32_16x16x32_bf16 v[96:99], v[248:251], v[8:11], v[96:99]
	ds_read_b128 v[244:247], v255 offset:4736
	s_waitcnt lgkmcnt(4)
	v_mfma_f32_16x16x32_bf16 v[100:103], v[228:231], v[4:7], v[180:183]
	ds_read_b128 v[248:251], v255 offset:4800
	s_waitcnt lgkmcnt(4)
	v_mfma_f32_16x16x32_bf16 v[100:103], v[232:235], v[8:11], v[100:103]
	ds_read_b128 v[228:231], v255 offset:9344
	s_waitcnt lgkmcnt(4)
	v_mfma_f32_16x16x32_bf16 v[104:107], v[236:239], v[12:15], v[204:207]
	ds_read_b128 v[232:235], v255 offset:9408
	s_waitcnt lgkmcnt(4)
	v_mfma_f32_16x16x32_bf16 v[104:107], v[240:243], v[16:19], v[104:107]
	ds_read_b128 v[236:239], v255 offset:13952
	s_waitcnt lgkmcnt(4)
	v_mfma_f32_16x16x32_bf16 v[108:111], v[244:247], v[12:15], v[208:211]
	ds_read_b128 v[240:243], v255 offset:14016
	s_waitcnt lgkmcnt(4)
	v_mfma_f32_16x16x32_bf16 v[108:111], v[248:251], v[16:19], v[108:111]
	ds_read_b64_tr_b16 v[244:245], v174 offset:36864
	ds_read_b64_tr_b16 v[246:247], v174 offset:41472
	s_waitcnt lgkmcnt(5)
	v_mfma_f32_16x16x32_bf16 v[112:115], v[228:231], v[12:15], v[184:187]
	ds_read_b64_tr_b16 v[248:249], v174 offset:36896
	ds_read_b64_tr_b16 v[250:251], v174 offset:41504
	s_waitcnt lgkmcnt(6)
	v_mfma_f32_16x16x32_bf16 v[112:115], v[232:235], v[16:19], v[112:115]
	ds_read_b64_tr_b16 v[228:229], v174 offset:36928
	ds_read_b64_tr_b16 v[230:231], v174 offset:41536
	s_waitcnt lgkmcnt(7)
	v_mfma_f32_16x16x32_bf16 v[116:119], v[236:239], v[12:15], v[188:191]
	ds_read_b64_tr_b16 v[232:233], v174 offset:36960
	ds_read_b64_tr_b16 v[234:235], v174 offset:41568
	s_waitcnt lgkmcnt(8)
	v_mfma_f32_16x16x32_bf16 v[116:119], v[240:243], v[16:19], v[116:119]
	ds_read_b64_tr_b16 v[236:237], v174 offset:36992
	ds_read_b64_tr_b16 v[238:239], v174 offset:41600
	s_waitcnt lgkmcnt(8)
	v_mfma_f32_16x16x32_bf16 v[28:31], v[244:247], v[120:123], v[28:31]
	v_mfma_f32_16x16x32_bf16 v[36:39], v[244:247], v[128:131], v[36:39]
	ds_read_b64_tr_b16 v[240:241], v174 offset:37024
	ds_read_b64_tr_b16 v[242:243], v174 offset:41632
	s_waitcnt lgkmcnt(8)
	v_mfma_f32_16x16x32_bf16 v[32:35], v[248:251], v[120:123], v[32:35]
	v_mfma_f32_16x16x32_bf16 v[44:47], v[248:251], v[128:131], v[44:47]
	ds_read_b64_tr_b16 v[244:245], v174 offset:37056
	ds_read_b64_tr_b16 v[246:247], v174 offset:41664
	s_waitcnt lgkmcnt(8)
	v_mfma_f32_16x16x32_bf16 v[40:43], v[228:231], v[120:123], v[40:43]
	v_mfma_f32_16x16x32_bf16 v[48:51], v[228:231], v[128:131], v[48:51]
	ds_read_b64_tr_b16 v[248:249], v174 offset:37088
	ds_read_b64_tr_b16 v[250:251], v174 offset:41696
	s_waitcnt lgkmcnt(8)
	v_mfma_f32_16x16x32_bf16 v[52:55], v[232:235], v[120:123], v[52:55]
	v_mfma_f32_16x16x32_bf16 v[60:63], v[232:235], v[128:131], v[60:63]
	ds_read_b64_tr_b16 v[228:229], v174 offset:46080
	ds_read_b64_tr_b16 v[230:231], v174 offset:50688
	s_waitcnt lgkmcnt(8)
	v_mfma_f32_16x16x32_bf16 v[56:59], v[236:239], v[120:123], v[56:59]
	v_mfma_f32_16x16x32_bf16 v[68:71], v[236:239], v[128:131], v[68:71]
	ds_read_b64_tr_b16 v[232:233], v174 offset:46112
	ds_read_b64_tr_b16 v[234:235], v174 offset:50720
	s_waitcnt lgkmcnt(8)
	v_mfma_f32_16x16x32_bf16 v[64:67], v[240:243], v[120:123], v[64:67]
	v_mfma_f32_16x16x32_bf16 v[76:79], v[240:243], v[128:131], v[76:79]
	ds_read_b64_tr_b16 v[236:237], v174 offset:46144
	ds_read_b64_tr_b16 v[238:239], v174 offset:50752
	s_waitcnt lgkmcnt(8)
	v_mfma_f32_16x16x32_bf16 v[72:75], v[244:247], v[120:123], v[72:75]
	v_mfma_f32_16x16x32_bf16 v[80:83], v[244:247], v[128:131], v[80:83]
	ds_read_b64_tr_b16 v[240:241], v174 offset:46176
	ds_read_b64_tr_b16 v[242:243], v174 offset:50784
	s_waitcnt lgkmcnt(8)
	v_mfma_f32_16x16x32_bf16 v[84:87], v[248:251], v[120:123], v[84:87]
	v_mfma_f32_16x16x32_bf16 v[20:23], v[248:251], v[128:131], v[20:23]
	ds_read_b64_tr_b16 v[244:245], v174 offset:46208
	ds_read_b64_tr_b16 v[246:247], v174 offset:50816
	s_waitcnt lgkmcnt(8)
	v_mfma_f32_16x16x32_bf16 v[28:31], v[228:231], v[124:127], v[28:31]
	v_mfma_f32_16x16x32_bf16 v[36:39], v[228:231], v[152:155], v[36:39]
	ds_read_b64_tr_b16 v[248:249], v174 offset:46240
	ds_read_b64_tr_b16 v[250:251], v174 offset:50848
	s_waitcnt lgkmcnt(8)
	v_mfma_f32_16x16x32_bf16 v[32:35], v[232:235], v[124:127], v[32:35]
	v_mfma_f32_16x16x32_bf16 v[44:47], v[232:235], v[152:155], v[44:47]
	ds_read_b64_tr_b16 v[228:229], v174 offset:46272
	ds_read_b64_tr_b16 v[230:231], v174 offset:50880
	s_waitcnt lgkmcnt(8)
	v_mfma_f32_16x16x32_bf16 v[40:43], v[236:239], v[124:127], v[40:43]
	v_mfma_f32_16x16x32_bf16 v[48:51], v[236:239], v[152:155], v[48:51]
	ds_read_b64_tr_b16 v[232:233], v174 offset:46304
	ds_read_b64_tr_b16 v[234:235], v174 offset:50912
	s_waitcnt lgkmcnt(8)
	v_mfma_f32_16x16x32_bf16 v[52:55], v[240:243], v[124:127], v[52:55]
	v_mfma_f32_16x16x32_bf16 v[60:63], v[240:243], v[152:155], v[60:63]
	s_waitcnt lgkmcnt(6)
	v_mfma_f32_16x16x32_bf16 v[56:59], v[244:247], v[124:127], v[56:59]
	v_mfma_f32_16x16x32_bf16 v[68:71], v[244:247], v[152:155], v[68:71]
	s_waitcnt lgkmcnt(4)
	v_mfma_f32_16x16x32_bf16 v[64:67], v[248:251], v[124:127], v[64:67]
	v_mfma_f32_16x16x32_bf16 v[76:79], v[248:251], v[152:155], v[76:79]
	s_waitcnt lgkmcnt(2)
	v_mfma_f32_16x16x32_bf16 v[72:75], v[228:231], v[124:127], v[72:75]
	v_mfma_f32_16x16x32_bf16 v[80:83], v[228:231], v[152:155], v[80:83]
	s_waitcnt lgkmcnt(0)
	v_mfma_f32_16x16x32_bf16 v[84:87], v[232:235], v[124:127], v[84:87]
	v_mfma_f32_16x16x32_bf16 v[20:23], v[232:235], v[152:155], v[20:23]
	s_waitcnt vmcnt(0)
	ds_write_b128 v169, v[212:215] offset:18432
	ds_write_b128 v169, v[216:219] offset:27648
	ds_write_b128 v164, v[220:223] offset:36864
	ds_write_b128 v164, v[224:227] offset:46080
	s_mov_b32 s31, s38
	s_mov_b32 s38, s39
	s_add_i32 s39, s39, 0x4800
	s_cmp_lg_u32 s39, 0xd800
	s_cselect_b32 s39, s39, 0
	s_mov_b32 s66, 0xff800000
	s_mov_b32 s67, 0xff800000
	s_cmp_ge_u32 s5, 1
	s_cselect_b32 s66, 0x5f800000, s66
	s_cselect_b32 s67, 0x42000000, s67
	s_add_i32 s5, s5, 1
	s_min_u32 s8, s5, 62
	s_add_i32 s8, s8, 1
	s_mul_i32 s30, s8, 0xf8000
	v_add_f32_e32 v165, 0x42800000, v165
	v_add_u32_e32 v174, s31, v168
	v_add_u32_e32 v164, s39, v169
	s_add_u32 s80, s42, s30
	s_addc_u32 s81, s43, 0
	s_add_u32 s86, s80, 0x7c000
	s_addc_u32 s87, s81, 0
	s_add_u32 s96, s46, s30
	s_addc_u32 s97, s47, 0
	s_add_u32 s98, s96, 0x7c000
	s_addc_u32 s99, s97, 0
	s_waitcnt lgkmcnt(0)
	s_barrier
	global_load_dwordx4 v[212:215], v173, s[80:81]
	global_load_dwordx4 v[220:223], v175, s[96:97]
	global_load_dwordx4 v[216:219], v173, s[86:87]
	global_load_dwordx4 v[224:227], v175, s[98:99]
	ds_read_b128 v[228:231], v255 offset:18432
	ds_read_b128 v[232:235], v255 offset:18496
	ds_read_b128 v[236:239], v255 offset:23040
	ds_read_b128 v[240:243], v255 offset:23104
	v_exp_f32_e32 v138, v88
	v_exp_f32_e32 v139, v89
	v_exp_f32_e32 v140, v90
	v_exp_f32_e32 v141, v91
	v_exp_f32_e32 v142, v92
	v_exp_f32_e32 v143, v93
	v_exp_f32_e32 v144, v94
	v_exp_f32_e32 v145, v95
	v_exp_f32_e32 v146, v96
	v_exp_f32_e32 v147, v97
	v_exp_f32_e32 v148, v98
	v_exp_f32_e32 v149, v99
	v_exp_f32_e32 v194, v100
	v_exp_f32_e32 v195, v101
	v_exp_f32_e32 v196, v102
	v_exp_f32_e32 v197, v103
	s_nop 0
	v_add_f32_e32 v26, v138, v139
	v_add_f32_e32 v26, v26, v140
	v_add_f32_e32 v26, v26, v141
	v_add_f32_e32 v26, v26, v142
	v_add_f32_e32 v26, v26, v143
	v_add_f32_e32 v26, v26, v144
	v_add_f32_e32 v26, v26, v145
	v_add_f32_e32 v26, v26, v146
	v_add_f32_e32 v26, v26, v147
	v_add_f32_e32 v26, v26, v148
	v_add_f32_e32 v26, v26, v149
	v_add_f32_e32 v26, v26, v194
	v_add_f32_e32 v26, v26, v195
	v_add_f32_e32 v26, v26, v196
	v_add_f32_e32 v26, v26, v197
	v_cmp_lt_f32_e32 vcc, s66, v26
	s_cbranch_vccnz .Ld_rare_B1_0

.Ld_back_B1_1:
	v_add_f32_e32 v151, v151, v26
	v_cvt_pk_bf16_f32 v128, v138, v139
	v_cvt_pk_bf16_f32 v129, v140, v141
	v_cvt_pk_bf16_f32 v130, v142, v143
	v_cvt_pk_bf16_f32 v131, v144, v145
	v_cvt_pk_bf16_f32 v152, v146, v147
	v_cvt_pk_bf16_f32 v153, v148, v149
	v_cvt_pk_bf16_f32 v154, v194, v195
	v_cvt_pk_bf16_f32 v155, v196, v197
	v_mov_b32_e32 v156, v165
	v_add_f32_e32 v157, 0x3f800000, v165
	v_add_f32_e32 v158, 0x40000000, v165
	v_add_f32_e32 v159, 0x40400000, v165
	v_add_f32_e32 v160, 0x41800000, v165
	v_add_f32_e32 v161, 0x41880000, v165
	v_add_f32_e32 v162, 0x41900000, v165
	v_add_f32_e32 v163, 0x41980000, v165
	v_add_f32_e32 v176, 0x42000000, v165
	v_add_f32_e32 v177, 0x42040000, v165
	v_add_f32_e32 v178, 0x42080000, v165
	v_add_f32_e32 v179, 0x420c0000, v165
	v_add_f32_e32 v180, 0x42400000, v165
	v_add_f32_e32 v181, 0x42440000, v165
	v_add_f32_e32 v182, 0x42480000, v165
	v_add_f32_e32 v183, 0x424c0000, v165
	v_fma_f32 v204, -v150, |v156|, v25
	v_fma_f32 v205, -v150, |v157|, v25
	v_fma_f32 v206, -v150, |v158|, v25
	v_fma_f32 v207, -v150, |v159|, v25
	v_fma_f32 v208, -v150, |v160|, v25
	v_fma_f32 v209, -v150, |v161|, v25
	v_fma_f32 v210, -v150, |v162|, v25
	v_fma_f32 v211, -v150, |v163|, v25
	v_fma_f32 v184, -v150, |v176|, v25
	v_fma_f32 v185, -v150, |v177|, v25
	v_fma_f32 v186, -v150, |v178|, v25
	v_fma_f32 v187, -v150, |v179|, v25
	v_fma_f32 v188, -v150, |v180|, v25
	v_fma_f32 v189, -v150, |v181|, v25
	v_fma_f32 v190, -v150, |v182|, v25
	v_fma_f32 v191, -v150, |v183|, v25
	v_fma_f32 v156, -v150, |v156|, v24
	v_fma_f32 v157, -v150, |v157|, v24
	v_fma_f32 v158, -v150, |v158|, v24
	v_fma_f32 v159, -v150, |v159|, v24
	v_fma_f32 v160, -v150, |v160|, v24
	v_fma_f32 v161, -v150, |v161|, v24
	v_fma_f32 v162, -v150, |v162|, v24
	v_fma_f32 v163, -v150, |v163|, v24
	v_fma_f32 v176, -v150, |v176|, v24
	v_fma_f32 v177, -v150, |v177|, v24
	v_fma_f32 v178, -v150, |v178|, v24
	v_fma_f32 v179, -v150, |v179|, v24
	v_fma_f32 v180, -v150, |v180|, v24
	v_fma_f32 v181, -v150, |v181|, v24
	v_fma_f32 v182, -v150, |v182|, v24
	v_fma_f32 v183, -v150, |v183|, v24
	ds_read_b128 v[244:247], v255 offset:27648
	s_waitcnt lgkmcnt(4)
	v_mfma_f32_16x16x32_bf16 v[88:91], v[228:231], v[4:7], v[156:159]
	ds_read_b128 v[248:251], v255 offset:27712
	s_waitcnt lgkmcnt(4)
	v_mfma_f32_16x16x32_bf16 v[88:91], v[232:235], v[8:11], v[88:91]
	ds_read_b128 v[228:231], v255 offset:32256
	s_waitcnt lgkmcnt(4)
	v_mfma_f32_16x16x32_bf16 v[92:95], v[236:239], v[4:7], v[160:163]
	ds_read_b128 v[232:235], v255 offset:32320
	s_waitcnt lgkmcnt(4)
	v_mfma_f32_16x16x32_bf16 v[92:95], v[240:243], v[8:11], v[92:95]
	ds_read_b128 v[236:239], v255 offset:18560
	s_waitcnt lgkmcnt(4)
	v_mfma_f32_16x16x32_bf16 v[96:99], v[244:247], v[4:7], v[176:179]
	ds_read_b128 v[240:243], v255 offset:18624
	s_waitcnt lgkmcnt(4)
	v_mfma_f32_16x16x32_bf16 v[96:99], v[248:251], v[8:11], v[96:99]
	ds_read_b128 v[244:247], v255 offset:23168
	s_waitcnt lgkmcnt(4)
	v_mfma_f32_16x16x32_bf16 v[100:103], v[228:231], v[4:7], v[180:183]
	ds_read_b128 v[248:251], v255 offset:23232
	s_waitcnt lgkmcnt(4)
	v_mfma_f32_16x16x32_bf16 v[100:103], v[232:235], v[8:11], v[100:103]
	ds_read_b128 v[228:231], v255 offset:27776
	s_waitcnt lgkmcnt(4)
	v_mfma_f32_16x16x32_bf16 v[104:107], v[236:239], v[12:15], v[204:207]
	ds_read_b128 v[232:235], v255 offset:27840
	s_waitcnt lgkmcnt(4)
	v_mfma_f32_16x16x32_bf16 v[104:107], v[240:243], v[16:19], v[104:107]
	ds_read_b128 v[236:239], v255 offset:32384
	s_waitcnt lgkmcnt(4)
	v_mfma_f32_16x16x32_bf16 v[108:111], v[244:247], v[12:15], v[208:211]
	ds_read_b128 v[240:243], v255 offset:32448
	s_waitcnt lgkmcnt(4)
	v_mfma_f32_16x16x32_bf16 v[108:111], v[248:251], v[16:19], v[108:111]
	ds_read_b64_tr_b16 v[244:245], v174 offset:36864
	ds_read_b64_tr_b16 v[246:247], v174 offset:41472
	s_waitcnt lgkmcnt(5)
	v_mfma_f32_16x16x32_bf16 v[112:115], v[228:231], v[12:15], v[184:187]
	ds_read_b64_tr_b16 v[248:249], v174 offset:36896
	ds_read_b64_tr_b16 v[250:251], v174 offset:41504
	s_waitcnt lgkmcnt(6)
	v_mfma_f32_16x16x32_bf16 v[112:115], v[232:235], v[16:19], v[112:115]
	ds_read_b64_tr_b16 v[228:229], v174 offset:36928
	ds_read_b64_tr_b16 v[230:231], v174 offset:41536
	s_waitcnt lgkmcnt(7)
	v_mfma_f32_16x16x32_bf16 v[116:119], v[236:239], v[12:15], v[188:191]
	ds_read_b64_tr_b16 v[232:233], v174 offset:36960
	ds_read_b64_tr_b16 v[234:235], v174 offset:41568
	s_waitcnt lgkmcnt(8)
	v_mfma_f32_16x16x32_bf16 v[116:119], v[240:243], v[16:19], v[116:119]
	ds_read_b64_tr_b16 v[236:237], v174 offset:36992
	ds_read_b64_tr_b16 v[238:239], v174 offset:41600
	s_waitcnt lgkmcnt(8)
	v_mfma_f32_16x16x32_bf16 v[28:31], v[244:247], v[120:123], v[28:31]
	v_mfma_f32_16x16x32_bf16 v[36:39], v[244:247], v[128:131], v[36:39]
	ds_read_b64_tr_b16 v[240:241], v174 offset:37024
	ds_read_b64_tr_b16 v[242:243], v174 offset:41632
	s_waitcnt lgkmcnt(8)
	v_mfma_f32_16x16x32_bf16 v[32:35], v[248:251], v[120:123], v[32:35]
	v_mfma_f32_16x16x32_bf16 v[44:47], v[248:251], v[128:131], v[44:47]
	ds_read_b64_tr_b16 v[244:245], v174 offset:37056
	ds_read_b64_tr_b16 v[246:247], v174 offset:41664
	s_waitcnt lgkmcnt(8)
	v_mfma_f32_16x16x32_bf16 v[40:43], v[228:231], v[120:123], v[40:43]
	v_mfma_f32_16x16x32_bf16 v[48:51], v[228:231], v[128:131], v[48:51]
	ds_read_b64_tr_b16 v[248:249], v174 offset:37088
	ds_read_b64_tr_b16 v[250:251], v174 offset:41696
	s_waitcnt lgkmcnt(8)
	v_mfma_f32_16x16x32_bf16 v[52:55], v[232:235], v[120:123], v[52:55]
	v_mfma_f32_16x16x32_bf16 v[60:63], v[232:235], v[128:131], v[60:63]
	ds_read_b64_tr_b16 v[228:229], v174 offset:46080
	ds_read_b64_tr_b16 v[230:231], v174 offset:50688
	s_waitcnt lgkmcnt(8)
	v_mfma_f32_16x16x32_bf16 v[56:59], v[236:239], v[120:123], v[56:59]
	v_mfma_f32_16x16x32_bf16 v[68:71], v[236:239], v[128:131], v[68:71]
	ds_read_b64_tr_b16 v[232:233], v174 offset:46112
	ds_read_b64_tr_b16 v[234:235], v174 offset:50720
	s_waitcnt lgkmcnt(8)
	v_mfma_f32_16x16x32_bf16 v[64:67], v[240:243], v[120:123], v[64:67]
	v_mfma_f32_16x16x32_bf16 v[76:79], v[240:243], v[128:131], v[76:79]
	ds_read_b64_tr_b16 v[236:237], v174 offset:46144
	ds_read_b64_tr_b16 v[238:239], v174 offset:50752
	s_waitcnt lgkmcnt(8)
	v_mfma_f32_16x16x32_bf16 v[72:75], v[244:247], v[120:123], v[72:75]
	v_mfma_f32_16x16x32_bf16 v[80:83], v[244:247], v[128:131], v[80:83]
	ds_read_b64_tr_b16 v[240:241], v174 offset:46176
	ds_read_b64_tr_b16 v[242:243], v174 offset:50784
	s_waitcnt lgkmcnt(8)
	v_mfma_f32_16x16x32_bf16 v[84:87], v[248:251], v[120:123], v[84:87]
	v_mfma_f32_16x16x32_bf16 v[20:23], v[248:251], v[128:131], v[20:23]
	ds_read_b64_tr_b16 v[244:245], v174 offset:46208
	ds_read_b64_tr_b16 v[246:247], v174 offset:50816
	s_waitcnt lgkmcnt(8)
	v_mfma_f32_16x16x32_bf16 v[28:31], v[228:231], v[124:127], v[28:31]
	v_mfma_f32_16x16x32_bf16 v[36:39], v[228:231], v[152:155], v[36:39]
	ds_read_b64_tr_b16 v[248:249], v174 offset:46240
	ds_read_b64_tr_b16 v[250:251], v174 offset:50848
	s_waitcnt lgkmcnt(8)
	v_mfma_f32_16x16x32_bf16 v[32:35], v[232:235], v[124:127], v[32:35]
	v_mfma_f32_16x16x32_bf16 v[44:47], v[232:235], v[152:155], v[44:47]
	ds_read_b64_tr_b16 v[228:229], v174 offset:46272
	ds_read_b64_tr_b16 v[230:231], v174 offset:50880
	s_waitcnt lgkmcnt(8)
	v_mfma_f32_16x16x32_bf16 v[40:43], v[236:239], v[124:127], v[40:43]
	v_mfma_f32_16x16x32_bf16 v[48:51], v[236:239], v[152:155], v[48:51]
	ds_read_b64_tr_b16 v[232:233], v174 offset:46304
	ds_read_b64_tr_b16 v[234:235], v174 offset:50912
	s_waitcnt lgkmcnt(8)
	v_mfma_f32_16x16x32_bf16 v[52:55], v[240:243], v[124:127], v[52:55]
	v_mfma_f32_16x16x32_bf16 v[60:63], v[240:243], v[152:155], v[60:63]
	s_waitcnt lgkmcnt(6)
	v_mfma_f32_16x16x32_bf16 v[56:59], v[244:247], v[124:127], v[56:59]
	v_mfma_f32_16x16x32_bf16 v[68:71], v[244:247], v[152:155], v[68:71]
	s_waitcnt lgkmcnt(4)
	v_mfma_f32_16x16x32_bf16 v[64:67], v[248:251], v[124:127], v[64:67]
	v_mfma_f32_16x16x32_bf16 v[76:79], v[248:251], v[152:155], v[76:79]
	s_waitcnt lgkmcnt(2)
	v_mfma_f32_16x16x32_bf16 v[72:75], v[228:231], v[124:127], v[72:75]
	v_mfma_f32_16x16x32_bf16 v[80:83], v[228:231], v[152:155], v[80:83]
	s_waitcnt lgkmcnt(0)
	v_mfma_f32_16x16x32_bf16 v[84:87], v[232:235], v[124:127], v[84:87]
	v_mfma_f32_16x16x32_bf16 v[20:23], v[232:235], v[152:155], v[20:23]
	s_waitcnt vmcnt(0)
	ds_write_b128 v169, v[212:215] offset:0
	ds_write_b128 v169, v[216:219] offset:9216
	ds_write_b128 v164, v[220:223] offset:36864
	ds_write_b128 v164, v[224:227] offset:46080
	s_mov_b32 s31, s38
	s_mov_b32 s38, s39
	s_add_i32 s39, s39, 0x4800
	s_cmp_lg_u32 s39, 0xd800
	s_cselect_b32 s39, s39, 0
	s_mov_b32 s66, 0xff800000
	s_mov_b32 s67, 0xff800000
	s_cmp_ge_u32 s5, 1
	s_cselect_b32 s66, 0x5f800000, s66
	s_cselect_b32 s67, 0x42000000, s67
	s_add_i32 s5, s5, 1
	s_min_u32 s8, s5, 62
	s_add_i32 s8, s8, 1
	s_mul_i32 s30, s8, 0xf8000
	v_add_f32_e32 v165, 0x42800000, v165
	v_add_u32_e32 v174, s31, v168
	v_add_u32_e32 v164, s39, v169
	s_add_u32 s80, s42, s30
	s_addc_u32 s81, s43, 0
	s_add_u32 s86, s80, 0x7c000
	s_addc_u32 s87, s81, 0
	s_add_u32 s96, s46, s30
	s_addc_u32 s97, s47, 0
	s_add_u32 s98, s96, 0x7c000
	s_addc_u32 s99, s97, 0
	s_waitcnt lgkmcnt(0)
	s_barrier
	s_cmp_lt_u32 s5, 64
	s_cbranch_scc1 .Ld_loopB
	v_add_u32_e32 v174, s31, v168
	ds_read_b64_tr_b16 v[228:229], v174 offset:36864
	ds_read_b64_tr_b16 v[230:231], v174 offset:41472
	ds_read_b64_tr_b16 v[232:233], v174 offset:36896
	ds_read_b64_tr_b16 v[234:235], v174 offset:41504
	ds_read_b64_tr_b16 v[236:237], v174 offset:36928
	ds_read_b64_tr_b16 v[238:239], v174 offset:41536
	ds_read_b64_tr_b16 v[240:241], v174 offset:36960
	ds_read_b64_tr_b16 v[242:243], v174 offset:41568
	v_exp_f32_e32 v138, v88
	v_exp_f32_e32 v139, v89
	v_exp_f32_e32 v140, v90
	v_exp_f32_e32 v141, v91
	v_exp_f32_e32 v142, v92
	v_exp_f32_e32 v143, v93
	v_exp_f32_e32 v144, v94
	v_exp_f32_e32 v145, v95
	v_exp_f32_e32 v146, v96
	v_exp_f32_e32 v147, v97
	v_exp_f32_e32 v148, v98
	v_exp_f32_e32 v149, v99
	v_exp_f32_e32 v194, v100
	v_exp_f32_e32 v195, v101
	v_exp_f32_e32 v196, v102
	v_exp_f32_e32 v197, v103
	s_nop 0
	v_add_f32_e32 v26, v138, v139
	v_add_f32_e32 v26, v26, v140
	v_add_f32_e32 v26, v26, v141
	v_add_f32_e32 v26, v26, v142
	v_add_f32_e32 v26, v26, v143
	v_add_f32_e32 v26, v26, v144
	v_add_f32_e32 v26, v26, v145
	v_add_f32_e32 v26, v26, v146
	v_add_f32_e32 v26, v26, v147
	v_add_f32_e32 v26, v26, v148
	v_add_f32_e32 v26, v26, v149
	v_add_f32_e32 v26, v26, v194
	v_add_f32_e32 v26, v26, v195
	v_add_f32_e32 v26, v26, v196
	v_add_f32_e32 v26, v26, v197
	v_cmp_lt_f32_e32 vcc, s66, v26
	s_cbranch_vccnz .Ld_rare_Bt_0

.Ld_back_Bt_1:
	v_add_f32_e32 v151, v151, v26
	v_cvt_pk_bf16_f32 v128, v138, v139
	v_cvt_pk_bf16_f32 v129, v140, v141
	v_cvt_pk_bf16_f32 v130, v142, v143
	v_cvt_pk_bf16_f32 v131, v144, v145
	v_cvt_pk_bf16_f32 v152, v146, v147
	v_cvt_pk_bf16_f32 v153, v148, v149
	v_cvt_pk_bf16_f32 v154, v194, v195
	v_cvt_pk_bf16_f32 v155, v196, v197
	ds_read_b64_tr_b16 v[244:245], v174 offset:36992
	ds_read_b64_tr_b16 v[246:247], v174 offset:41600
	s_waitcnt lgkmcnt(8)
	v_mfma_f32_16x16x32_bf16 v[28:31], v[228:231], v[120:123], v[28:31]
	v_mfma_f32_16x16x32_bf16 v[36:39], v[228:231], v[128:131], v[36:39]
	ds_read_b64_tr_b16 v[248:249], v174 offset:37024
	ds_read_b64_tr_b16 v[250:251], v174 offset:41632
	s_waitcnt lgkmcnt(8)
	v_mfma_f32_16x16x32_bf16 v[32:35], v[232:235], v[120:123], v[32:35]
	v_mfma_f32_16x16x32_bf16 v[44:47], v[232:235], v[128:131], v[44:47]
	ds_read_b64_tr_b16 v[228:229], v174 offset:37056
	ds_read_b64_tr_b16 v[230:231], v174 offset:41664
	s_waitcnt lgkmcnt(8)
	v_mfma_f32_16x16x32_bf16 v[40:43], v[236:239], v[120:123], v[40:43]
	v_mfma_f32_16x16x32_bf16 v[48:51], v[236:239], v[128:131], v[48:51]
	ds_read_b64_tr_b16 v[232:233], v174 offset:37088
	ds_read_b64_tr_b16 v[234:235], v174 offset:41696
	s_waitcnt lgkmcnt(8)
	v_mfma_f32_16x16x32_bf16 v[52:55], v[240:243], v[120:123], v[52:55]
	v_mfma_f32_16x16x32_bf16 v[60:63], v[240:243], v[128:131], v[60:63]
	ds_read_b64_tr_b16 v[236:237], v174 offset:46080
	ds_read_b64_tr_b16 v[238:239], v174 offset:50688
	s_waitcnt lgkmcnt(8)
	v_mfma_f32_16x16x32_bf16 v[56:59], v[244:247], v[120:123], v[56:59]
	v_mfma_f32_16x16x32_bf16 v[68:71], v[244:247], v[128:131], v[68:71]
	ds_read_b64_tr_b16 v[240:241], v174 offset:46112
	ds_read_b64_tr_b16 v[242:243], v174 offset:50720
	s_waitcnt lgkmcnt(8)
	v_mfma_f32_16x16x32_bf16 v[64:67], v[248:251], v[120:123], v[64:67]
	v_mfma_f32_16x16x32_bf16 v[76:79], v[248:251], v[128:131], v[76:79]
	ds_read_b64_tr_b16 v[244:245], v174 offset:46144
	ds_read_b64_tr_b16 v[246:247], v174 offset:50752
	s_waitcnt lgkmcnt(8)
	v_mfma_f32_16x16x32_bf16 v[72:75], v[228:231], v[120:123], v[72:75]
	v_mfma_f32_16x16x32_bf16 v[80:83], v[228:231], v[128:131], v[80:83]
	ds_read_b64_tr_b16 v[248:249], v174 offset:46176
	ds_read_b64_tr_b16 v[250:251], v174 offset:50784
	s_waitcnt lgkmcnt(8)
	v_mfma_f32_16x16x32_bf16 v[84:87], v[232:235], v[120:123], v[84:87]
	v_mfma_f32_16x16x32_bf16 v[20:23], v[232:235], v[128:131], v[20:23]
	ds_read_b64_tr_b16 v[228:229], v174 offset:46208
	ds_read_b64_tr_b16 v[230:231], v174 offset:50816
	s_waitcnt lgkmcnt(8)
	v_mfma_f32_16x16x32_bf16 v[28:31], v[236:239], v[124:127], v[28:31]
	v_mfma_f32_16x16x32_bf16 v[36:39], v[236:239], v[152:155], v[36:39]
	ds_read_b64_tr_b16 v[232:233], v174 offset:46240
	ds_read_b64_tr_b16 v[234:235], v174 offset:50848
	s_waitcnt lgkmcnt(8)
	v_mfma_f32_16x16x32_bf16 v[32:35], v[240:243], v[124:127], v[32:35]
	v_mfma_f32_16x16x32_bf16 v[44:47], v[240:243], v[152:155], v[44:47]
	ds_read_b64_tr_b16 v[236:237], v174 offset:46272
	ds_read_b64_tr_b16 v[238:239], v174 offset:50880
	s_waitcnt lgkmcnt(8)
	v_mfma_f32_16x16x32_bf16 v[40:43], v[244:247], v[124:127], v[40:43]
	v_mfma_f32_16x16x32_bf16 v[48:51], v[244:247], v[152:155], v[48:51]
	ds_read_b64_tr_b16 v[240:241], v174 offset:46304
	ds_read_b64_tr_b16 v[242:243], v174 offset:50912
	s_waitcnt lgkmcnt(8)
	v_mfma_f32_16x16x32_bf16 v[52:55], v[248:251], v[124:127], v[52:55]
	v_mfma_f32_16x16x32_bf16 v[60:63], v[248:251], v[152:155], v[60:63]
	s_waitcnt lgkmcnt(6)
	v_mfma_f32_16x16x32_bf16 v[56:59], v[228:231], v[124:127], v[56:59]
	v_mfma_f32_16x16x32_bf16 v[68:71], v[228:231], v[152:155], v[68:71]
	s_waitcnt lgkmcnt(4)
	v_mfma_f32_16x16x32_bf16 v[64:67], v[232:235], v[124:127], v[64:67]
	v_mfma_f32_16x16x32_bf16 v[76:79], v[232:235], v[152:155], v[76:79]
	s_waitcnt lgkmcnt(2)
	v_mfma_f32_16x16x32_bf16 v[72:75], v[236:239], v[124:127], v[72:75]
	v_mfma_f32_16x16x32_bf16 v[80:83], v[236:239], v[152:155], v[80:83]
	s_waitcnt lgkmcnt(0)
	v_mfma_f32_16x16x32_bf16 v[84:87], v[240:243], v[124:127], v[84:87]
	v_mfma_f32_16x16x32_bf16 v[20:23], v[240:243], v[152:155], v[20:23]
	v_mov_b32_e32 v138, 0xa00
	v_mov_b32_e32 v139, 0x0
	v_mov_b32_e32 v140, 0x9ff
	v_mov_b32_e32 v141, 0x0
	v_mov_b32_e32 v142, 0x200
	v_mov_b32_e32 v143, 0x0
	v_mov_b32_e32 v144, 0x1ff
	v_mov_b32_e32 v145, 0x0
	v_mov_b32_e32 v146, 0xb00
	v_mov_b32_e32 v147, 0x0
	v_mov_b32_e32 v148, 0xaff
	v_mov_b32_e32 v149, 0x0
	v_mov_b32_e32 v194, 0x358637bd
	v_mov_b32_e32 v195, 0x2000
	v_mov_b32_e32 v196, 0x3e38aa3b
	v_mov_b32_e32 v197, 0x41b17218
	s_branch .LBB0_634
.Ld_rare_B0_0:
	v_max3_f32 v26, v88, v89, v90
	v_max3_f32 v26, v26, v91, v92
	v_max3_f32 v26, v26, v93, v94
	v_max3_f32 v26, v26, v95, v96
	v_max3_f32 v26, v26, v97, v98
	v_max3_f32 v26, v26, v99, v100
	v_max3_f32 v26, v26, v101, v102
	v_max_f32_e32 v26, v26, v103
	v_mov_b32_e32 v27, v26
	s_nop 1
	v_permlane16_swap_b32_e32 v26, v27
	v_max_f32_e32 v26, v26, v27
	v_mov_b32_e32 v27, v26
	s_nop 1
	v_permlane32_swap_b32_e32 v26, v27
	v_max_f32_e32 v26, v26, v27
	v_cmp_lt_f32_e32 vcc, s67, v26
	s_nop 1
	v_cndmask_b32_e32 v3, 0, v26, vcc
	v_sub_f32_e32 v2, 0, v3
	v_min_f32_e32 v2, 0, v2
	v_exp_f32_e32 v2, v2
	v_sub_f32_e32 v24, v24, v3
	v_mul_f32_e32 v0, v0, v2
	v_mul_f32_e32 v28, v28, v2
	v_mul_f32_e32 v29, v29, v2
	v_mul_f32_e32 v30, v30, v2
	v_mul_f32_e32 v31, v31, v2
	v_mul_f32_e32 v32, v32, v2
	v_mul_f32_e32 v33, v33, v2
	v_mul_f32_e32 v34, v34, v2
	v_mul_f32_e32 v35, v35, v2
	v_mul_f32_e32 v40, v40, v2
	v_mul_f32_e32 v41, v41, v2
	v_mul_f32_e32 v42, v42, v2
	v_mul_f32_e32 v43, v43, v2
	v_mul_f32_e32 v52, v52, v2
	v_mul_f32_e32 v53, v53, v2
	v_mul_f32_e32 v54, v54, v2
	v_mul_f32_e32 v55, v55, v2
	v_mul_f32_e32 v56, v56, v2
	v_mul_f32_e32 v57, v57, v2
	v_mul_f32_e32 v58, v58, v2
	v_mul_f32_e32 v59, v59, v2
	v_mul_f32_e32 v64, v64, v2
	v_mul_f32_e32 v65, v65, v2
	v_mul_f32_e32 v66, v66, v2
	v_mul_f32_e32 v67, v67, v2
	v_mul_f32_e32 v72, v72, v2
	v_mul_f32_e32 v73, v73, v2
	v_mul_f32_e32 v74, v74, v2
	v_mul_f32_e32 v75, v75, v2
	v_mul_f32_e32 v84, v84, v2
	v_mul_f32_e32 v85, v85, v2
	v_mul_f32_e32 v86, v86, v2
	v_mul_f32_e32 v87, v87, v2
	v_sub_f32_e32 v88, v88, v3
	v_sub_f32_e32 v89, v89, v3
	v_sub_f32_e32 v90, v90, v3
	v_sub_f32_e32 v91, v91, v3
	v_sub_f32_e32 v92, v92, v3
	v_sub_f32_e32 v93, v93, v3
	v_sub_f32_e32 v94, v94, v3
	v_sub_f32_e32 v95, v95, v3
	v_sub_f32_e32 v96, v96, v3
	v_sub_f32_e32 v97, v97, v3
	v_sub_f32_e32 v98, v98, v3
	v_sub_f32_e32 v99, v99, v3
	v_sub_f32_e32 v100, v100, v3
	v_sub_f32_e32 v101, v101, v3
	v_sub_f32_e32 v102, v102, v3
	v_sub_f32_e32 v103, v103, v3
	v_exp_f32_e32 v138, v88
	v_exp_f32_e32 v139, v89
	v_exp_f32_e32 v140, v90
	v_exp_f32_e32 v141, v91
	v_exp_f32_e32 v142, v92
	v_exp_f32_e32 v143, v93
	v_exp_f32_e32 v144, v94
	v_exp_f32_e32 v145, v95
	v_exp_f32_e32 v146, v96
	v_exp_f32_e32 v147, v97
	v_exp_f32_e32 v148, v98
	v_exp_f32_e32 v149, v99
	v_exp_f32_e32 v194, v100
	v_exp_f32_e32 v195, v101
	v_exp_f32_e32 v196, v102
	v_exp_f32_e32 v197, v103
	s_nop 0
	v_add_f32_e32 v26, v138, v139
	v_add_f32_e32 v26, v26, v140
	v_add_f32_e32 v26, v26, v141
	v_add_f32_e32 v26, v26, v142
	v_add_f32_e32 v26, v26, v143
	v_add_f32_e32 v26, v26, v144
	v_add_f32_e32 v26, v26, v145
	v_add_f32_e32 v26, v26, v146
	v_add_f32_e32 v26, v26, v147
	v_add_f32_e32 v26, v26, v148
	v_add_f32_e32 v26, v26, v149
	v_add_f32_e32 v26, v26, v194
	v_add_f32_e32 v26, v26, v195
	v_add_f32_e32 v26, v26, v196
	v_add_f32_e32 v26, v26, v197
	s_branch .Ld_back_B0_0
.Ld_rare_B0_1:
	v_max3_f32 v26, v104, v105, v106
	v_max3_f32 v26, v26, v107, v108
	v_max3_f32 v26, v26, v109, v110
	v_max3_f32 v26, v26, v111, v112
	v_max3_f32 v26, v26, v113, v114
	v_max3_f32 v26, v26, v115, v116
	v_max3_f32 v26, v26, v117, v118
	v_max_f32_e32 v26, v26, v119
	v_mov_b32_e32 v27, v26
	s_nop 1
	v_permlane16_swap_b32_e32 v26, v27
	v_max_f32_e32 v26, v26, v27
	v_mov_b32_e32 v27, v26
	s_nop 1
	v_permlane32_swap_b32_e32 v26, v27
	v_max_f32_e32 v26, v26, v27
	v_cmp_lt_f32_e32 vcc, s67, v26
	s_nop 1
	v_cndmask_b32_e32 v3, 0, v26, vcc
	v_sub_f32_e32 v2, 0, v3
	v_min_f32_e32 v2, 0, v2
	v_exp_f32_e32 v2, v2
	v_sub_f32_e32 v25, v25, v3
	v_mul_f32_e32 v151, v151, v2
	v_mul_f32_e32 v36, v36, v2
	v_mul_f32_e32 v37, v37, v2
	v_mul_f32_e32 v38, v38, v2
	v_mul_f32_e32 v39, v39, v2
	v_mul_f32_e32 v44, v44, v2
	v_mul_f32_e32 v45, v45, v2
	v_mul_f32_e32 v46, v46, v2
	v_mul_f32_e32 v47, v47, v2
	v_mul_f32_e32 v48, v48, v2
	v_mul_f32_e32 v49, v49, v2
	v_mul_f32_e32 v50, v50, v2
	v_mul_f32_e32 v51, v51, v2
	v_mul_f32_e32 v60, v60, v2
	v_mul_f32_e32 v61, v61, v2
	v_mul_f32_e32 v62, v62, v2
	v_mul_f32_e32 v63, v63, v2
	v_mul_f32_e32 v68, v68, v2
	v_mul_f32_e32 v69, v69, v2
	v_mul_f32_e32 v70, v70, v2
	v_mul_f32_e32 v71, v71, v2
	v_mul_f32_e32 v76, v76, v2
	v_mul_f32_e32 v77, v77, v2
	v_mul_f32_e32 v78, v78, v2
	v_mul_f32_e32 v79, v79, v2
	v_mul_f32_e32 v80, v80, v2
	v_mul_f32_e32 v81, v81, v2
	v_mul_f32_e32 v82, v82, v2
	v_mul_f32_e32 v83, v83, v2
	v_mul_f32_e32 v20, v20, v2
	v_mul_f32_e32 v21, v21, v2
	v_mul_f32_e32 v22, v22, v2
	v_mul_f32_e32 v23, v23, v2
	v_sub_f32_e32 v104, v104, v3
	v_sub_f32_e32 v105, v105, v3
	v_sub_f32_e32 v106, v106, v3
	v_sub_f32_e32 v107, v107, v3
	v_sub_f32_e32 v108, v108, v3
	v_sub_f32_e32 v109, v109, v3
	v_sub_f32_e32 v110, v110, v3
	v_sub_f32_e32 v111, v111, v3
	v_sub_f32_e32 v112, v112, v3
	v_sub_f32_e32 v113, v113, v3
	v_sub_f32_e32 v114, v114, v3
	v_sub_f32_e32 v115, v115, v3
	v_sub_f32_e32 v116, v116, v3
	v_sub_f32_e32 v117, v117, v3
	v_sub_f32_e32 v118, v118, v3
	v_sub_f32_e32 v119, v119, v3
	v_exp_f32_e32 v138, v104
	v_exp_f32_e32 v139, v105
	v_exp_f32_e32 v140, v106
	v_exp_f32_e32 v141, v107
	v_exp_f32_e32 v142, v108
	v_exp_f32_e32 v143, v109
	v_exp_f32_e32 v144, v110
	v_exp_f32_e32 v145, v111
	v_exp_f32_e32 v146, v112
	v_exp_f32_e32 v147, v113
	v_exp_f32_e32 v148, v114
	v_exp_f32_e32 v149, v115
	v_exp_f32_e32 v194, v116
	v_exp_f32_e32 v195, v117
	v_exp_f32_e32 v196, v118
	v_exp_f32_e32 v197, v119
	s_nop 0
	v_add_f32_e32 v26, v138, v139
	v_add_f32_e32 v26, v26, v140
	v_add_f32_e32 v26, v26, v141
	v_add_f32_e32 v26, v26, v142
	v_add_f32_e32 v26, v26, v143
	v_add_f32_e32 v26, v26, v144
	v_add_f32_e32 v26, v26, v145
	v_add_f32_e32 v26, v26, v146
	v_add_f32_e32 v26, v26, v147
	v_add_f32_e32 v26, v26, v148
	v_add_f32_e32 v26, v26, v149
	v_add_f32_e32 v26, v26, v194
	v_add_f32_e32 v26, v26, v195
	v_add_f32_e32 v26, v26, v196
	v_add_f32_e32 v26, v26, v197
	s_branch .Ld_back_B0_1

.Ld_groupA:
	v_mov_b32_e32 v28, 0
	v_mov_b32_e32 v29, 0
	v_mov_b32_e32 v30, 0
	v_mov_b32_e32 v31, 0
	v_mov_b32_e32 v32, 0
	v_mov_b32_e32 v33, 0
	v_mov_b32_e32 v34, 0
	v_mov_b32_e32 v35, 0
	v_mov_b32_e32 v40, 0
	v_mov_b32_e32 v41, 0
	v_mov_b32_e32 v42, 0
	v_mov_b32_e32 v43, 0
	v_mov_b32_e32 v52, 0
	v_mov_b32_e32 v53, 0
	v_mov_b32_e32 v54, 0
	v_mov_b32_e32 v55, 0
	v_mov_b32_e32 v56, 0
	v_mov_b32_e32 v57, 0
	v_mov_b32_e32 v58, 0
	v_mov_b32_e32 v59, 0
	v_mov_b32_e32 v64, 0
	v_mov_b32_e32 v65, 0
	v_mov_b32_e32 v66, 0
	v_mov_b32_e32 v67, 0
	v_mov_b32_e32 v72, 0
	v_mov_b32_e32 v73, 0
	v_mov_b32_e32 v74, 0
	v_mov_b32_e32 v75, 0
	v_mov_b32_e32 v84, 0
	v_mov_b32_e32 v85, 0
	v_mov_b32_e32 v86, 0
	v_mov_b32_e32 v87, 0
	v_mov_b32_e32 v36, 0
	v_mov_b32_e32 v37, 0
	v_mov_b32_e32 v38, 0
	v_mov_b32_e32 v39, 0
	v_mov_b32_e32 v44, 0
	v_mov_b32_e32 v45, 0
	v_mov_b32_e32 v46, 0
	v_mov_b32_e32 v47, 0
	v_mov_b32_e32 v48, 0
	v_mov_b32_e32 v49, 0
	v_mov_b32_e32 v50, 0
	v_mov_b32_e32 v51, 0
	v_mov_b32_e32 v60, 0
	v_mov_b32_e32 v61, 0
	v_mov_b32_e32 v62, 0
	v_mov_b32_e32 v63, 0
	v_mov_b32_e32 v68, 0
	v_mov_b32_e32 v69, 0
	v_mov_b32_e32 v70, 0
	v_mov_b32_e32 v71, 0
	v_mov_b32_e32 v76, 0
	v_mov_b32_e32 v77, 0
	v_mov_b32_e32 v78, 0
	v_mov_b32_e32 v79, 0
	v_mov_b32_e32 v80, 0
	v_mov_b32_e32 v81, 0
	v_mov_b32_e32 v82, 0
	v_mov_b32_e32 v83, 0
	v_mov_b32_e32 v20, 0
	v_mov_b32_e32 v21, 0
	v_mov_b32_e32 v22, 0
	v_mov_b32_e32 v23, 0
	v_mov_b32_e32 v120, 0
	v_mov_b32_e32 v121, 0
	v_mov_b32_e32 v122, 0
	v_mov_b32_e32 v123, 0
	v_mov_b32_e32 v124, 0
	v_mov_b32_e32 v125, 0
	v_mov_b32_e32 v126, 0
	v_mov_b32_e32 v127, 0
	v_mov_b32_e32 v128, 0
	v_mov_b32_e32 v129, 0
	v_mov_b32_e32 v130, 0
	v_mov_b32_e32 v131, 0
	v_mov_b32_e32 v152, 0
	v_mov_b32_e32 v153, 0
	v_mov_b32_e32 v154, 0
	v_mov_b32_e32 v155, 0
	v_mov_b32_e32 v0, 0
	v_mov_b32_e32 v151, 0
	v_mov_b32_e32 v24, 0
	v_mov_b32_e32 v25, 0
	s_mov_b32 s66, 0xff800000
	s_mov_b32 s67, 0xff800000
	v_add_u32_e32 v255, v171, v172
	v_mov_b32_e32 v165, v170
	v_readfirstlane_b32 s42, v134
	v_readfirstlane_b32 s43, v135
	v_readfirstlane_b32 s46, v136
	v_readfirstlane_b32 s47, v137
	s_nop 3
	v_subrev_u32_e32 v173, s42, v134
	v_subrev_u32_e32 v175, s46, v136
	s_mov_b32 s5, 0
	s_mov_b32 s31, 0
	s_mov_b32 s38, 0
	s_mov_b32 s39, 0x4800
	s_mov_b32 s30, 0xf8000
	v_add_u32_e32 v174, s31, v168
	v_add_u32_e32 v164, s39, v169
	s_add_u32 s80, s42, s30
	s_addc_u32 s81, s43, 0
	s_add_u32 s86, s80, 0x7c000
	s_addc_u32 s87, s81, 0
	s_add_u32 s96, s46, s30
	s_addc_u32 s97, s47, 0
	s_add_u32 s98, s96, 0x7c000
	s_addc_u32 s99, s97, 0
	v_mov_b32_e32 v156, v165
	v_add_f32_e32 v157, 0x3f800000, v165
	v_add_f32_e32 v158, 0x40000000, v165
	v_add_f32_e32 v159, 0x40400000, v165
	v_add_f32_e32 v160, 0x41800000, v165
	v_add_f32_e32 v161, 0x41880000, v165
	v_add_f32_e32 v162, 0x41900000, v165
	v_add_f32_e32 v163, 0x41980000, v165
	v_add_f32_e32 v176, 0x42000000, v165
	v_add_f32_e32 v177, 0x42040000, v165
	v_add_f32_e32 v178, 0x42080000, v165
	v_add_f32_e32 v179, 0x420c0000, v165
	v_add_f32_e32 v180, 0x42400000, v165
	v_add_f32_e32 v181, 0x42440000, v165
	v_add_f32_e32 v182, 0x42480000, v165
	v_add_f32_e32 v183, 0x424c0000, v165
	v_fma_f32 v204, -v150, |v156|, v25
	v_fma_f32 v205, -v150, |v157|, v25
	v_fma_f32 v206, -v150, |v158|, v25
	v_fma_f32 v207, -v150, |v159|, v25
	v_fma_f32 v208, -v150, |v160|, v25
	v_fma_f32 v209, -v150, |v161|, v25
	v_fma_f32 v210, -v150, |v162|, v25
	v_fma_f32 v211, -v150, |v163|, v25
	v_fma_f32 v184, -v150, |v176|, v25
	v_fma_f32 v185, -v150, |v177|, v25
	v_fma_f32 v186, -v150, |v178|, v25
	v_fma_f32 v187, -v150, |v179|, v25
	v_fma_f32 v188, -v150, |v180|, v25
	v_fma_f32 v189, -v150, |v181|, v25
	v_fma_f32 v190, -v150, |v182|, v25
	v_fma_f32 v191, -v150, |v183|, v25
	v_fma_f32 v156, -v150, |v156|, v24
	v_fma_f32 v157, -v150, |v157|, v24
	v_fma_f32 v158, -v150, |v158|, v24
	v_fma_f32 v159, -v150, |v159|, v24
	v_fma_f32 v160, -v150, |v160|, v24
	v_fma_f32 v161, -v150, |v161|, v24
	v_fma_f32 v162, -v150, |v162|, v24
	v_fma_f32 v163, -v150, |v163|, v24
	v_fma_f32 v176, -v150, |v176|, v24
	v_fma_f32 v177, -v150, |v177|, v24
	v_fma_f32 v178, -v150, |v178|, v24
	v_fma_f32 v179, -v150, |v179|, v24
	v_fma_f32 v180, -v150, |v180|, v24
	v_fma_f32 v181, -v150, |v181|, v24
	v_fma_f32 v182, -v150, |v182|, v24
	v_fma_f32 v183, -v150, |v183|, v24
.Ld_loopA:
	global_load_dwordx4 v[212:215], v173, s[80:81]
	global_load_dwordx4 v[220:223], v175, s[96:97]
	global_load_dwordx4 v[216:219], v173, s[86:87]
	global_load_dwordx4 v[224:227], v175, s[98:99]
	ds_read_b64_tr_b16 v[228:229], v174 offset:36864
	ds_read_b64_tr_b16 v[230:231], v174 offset:41472
	ds_read_b64_tr_b16 v[232:233], v174 offset:36896
	ds_read_b64_tr_b16 v[234:235], v174 offset:41504
	ds_read_b64_tr_b16 v[236:237], v174 offset:36928
	ds_read_b64_tr_b16 v[238:239], v174 offset:41536
	ds_read_b64_tr_b16 v[240:241], v174 offset:36960
	ds_read_b64_tr_b16 v[242:243], v174 offset:41568
	ds_read_b64_tr_b16 v[244:245], v174 offset:36992
	ds_read_b64_tr_b16 v[246:247], v174 offset:41600
	s_waitcnt lgkmcnt(8)
	v_mfma_f32_16x16x32_bf16 v[28:31], v[228:231], v[120:123], v[28:31]
	v_mfma_f32_16x16x32_bf16 v[36:39], v[228:231], v[128:131], v[36:39]
	ds_read_b64_tr_b16 v[248:249], v174 offset:37024
	ds_read_b64_tr_b16 v[250:251], v174 offset:41632
	s_waitcnt lgkmcnt(8)
	v_mfma_f32_16x16x32_bf16 v[32:35], v[232:235], v[120:123], v[32:35]
	v_mfma_f32_16x16x32_bf16 v[44:47], v[232:235], v[128:131], v[44:47]
	ds_read_b64_tr_b16 v[228:229], v174 offset:37056
	ds_read_b64_tr_b16 v[230:231], v174 offset:41664
	s_waitcnt lgkmcnt(8)
	v_mfma_f32_16x16x32_bf16 v[40:43], v[236:239], v[120:123], v[40:43]
	v_mfma_f32_16x16x32_bf16 v[48:51], v[236:239], v[128:131], v[48:51]
	ds_read_b64_tr_b16 v[232:233], v174 offset:37088
	ds_read_b64_tr_b16 v[234:235], v174 offset:41696
	s_waitcnt lgkmcnt(8)
	v_mfma_f32_16x16x32_bf16 v[52:55], v[240:243], v[120:123], v[52:55]
	v_mfma_f32_16x16x32_bf16 v[60:63], v[240:243], v[128:131], v[60:63]
	ds_read_b64_tr_b16 v[236:237], v174 offset:46080
	ds_read_b64_tr_b16 v[238:239], v174 offset:50688
	s_waitcnt lgkmcnt(8)
	v_mfma_f32_16x16x32_bf16 v[56:59], v[244:247], v[120:123], v[56:59]
	v_mfma_f32_16x16x32_bf16 v[68:71], v[244:247], v[128:131], v[68:71]
	ds_read_b64_tr_b16 v[240:241], v174 offset:46112
	ds_read_b64_tr_b16 v[242:243], v174 offset:50720
	s_waitcnt lgkmcnt(8)
	v_mfma_f32_16x16x32_bf16 v[64:67], v[248:251], v[120:123], v[64:67]
	v_mfma_f32_16x16x32_bf16 v[76:79], v[248:251], v[128:131], v[76:79]
	ds_read_b64_tr_b16 v[244:245], v174 offset:46144
	ds_read_b64_tr_b16 v[246:247], v174 offset:50752
	s_waitcnt lgkmcnt(8)
	v_mfma_f32_16x16x32_bf16 v[72:75], v[228:231], v[120:123], v[72:75]
	v_mfma_f32_16x16x32_bf16 v[80:83], v[228:231], v[128:131], v[80:83]
	ds_read_b64_tr_b16 v[248:249], v174 offset:46176
	ds_read_b64_tr_b16 v[250:251], v174 offset:50784
	s_waitcnt lgkmcnt(8)
	v_mfma_f32_16x16x32_bf16 v[84:87], v[232:235], v[120:123], v[84:87]
	v_mfma_f32_16x16x32_bf16 v[20:23], v[232:235], v[128:131], v[20:23]
	ds_read_b64_tr_b16 v[228:229], v174 offset:46208
	ds_read_b64_tr_b16 v[230:231], v174 offset:50816
	s_waitcnt lgkmcnt(8)
	v_mfma_f32_16x16x32_bf16 v[28:31], v[236:239], v[124:127], v[28:31]
	v_mfma_f32_16x16x32_bf16 v[36:39], v[236:239], v[152:155], v[36:39]
	ds_read_b64_tr_b16 v[232:233], v174 offset:46240
	ds_read_b64_tr_b16 v[234:235], v174 offset:50848
	s_waitcnt lgkmcnt(8)
	v_mfma_f32_16x16x32_bf16 v[32:35], v[240:243], v[124:127], v[32:35]
	v_mfma_f32_16x16x32_bf16 v[44:47], v[240:243], v[152:155], v[44:47]
	ds_read_b64_tr_b16 v[236:237], v174 offset:46272
	ds_read_b64_tr_b16 v[238:239], v174 offset:50880
	s_waitcnt lgkmcnt(8)
	v_mfma_f32_16x16x32_bf16 v[40:43], v[244:247], v[124:127], v[40:43]
	v_mfma_f32_16x16x32_bf16 v[48:51], v[244:247], v[152:155], v[48:51]
	ds_read_b64_tr_b16 v[240:241], v174 offset:46304
	ds_read_b64_tr_b16 v[242:243], v174 offset:50912
	s_waitcnt lgkmcnt(8)
	v_mfma_f32_16x16x32_bf16 v[52:55], v[248:251], v[124:127], v[52:55]
	v_mfma_f32_16x16x32_bf16 v[60:63], v[248:251], v[152:155], v[60:63]
	ds_read_b128 v[244:247], v255 offset:0
	s_waitcnt lgkmcnt(7)
	v_mfma_f32_16x16x32_bf16 v[56:59], v[228:231], v[124:127], v[56:59]
	v_mfma_f32_16x16x32_bf16 v[68:71], v[228:231], v[152:155], v[68:71]
	ds_read_b128 v[248:251], v255 offset:64
	s_waitcnt lgkmcnt(6)
	v_mfma_f32_16x16x32_bf16 v[64:67], v[232:235], v[124:127], v[64:67]
	v_mfma_f32_16x16x32_bf16 v[76:79], v[232:235], v[152:155], v[76:79]
	ds_read_b128 v[228:231], v255 offset:4608
	s_waitcnt lgkmcnt(5)
	v_mfma_f32_16x16x32_bf16 v[72:75], v[236:239], v[124:127], v[72:75]
	v_mfma_f32_16x16x32_bf16 v[80:83], v[236:239], v[152:155], v[80:83]
	ds_read_b128 v[232:235], v255 offset:4672
	s_waitcnt lgkmcnt(4)
	v_mfma_f32_16x16x32_bf16 v[84:87], v[240:243], v[124:127], v[84:87]
	v_mfma_f32_16x16x32_bf16 v[20:23], v[240:243], v[152:155], v[20:23]
	ds_read_b128 v[236:239], v255 offset:9216
	s_waitcnt lgkmcnt(4)
	v_mfma_f32_16x16x32_bf16 v[88:91], v[244:247], v[4:7], v[156:159]
	ds_read_b128 v[240:243], v255 offset:9280
	s_waitcnt lgkmcnt(4)
	v_mfma_f32_16x16x32_bf16 v[88:91], v[248:251], v[8:11], v[88:91]
	ds_read_b128 v[244:247], v255 offset:13824
	s_waitcnt lgkmcnt(4)
	v_mfma_f32_16x16x32_bf16 v[92:95], v[228:231], v[4:7], v[160:163]
	ds_read_b128 v[248:251], v255 offset:13888
	s_waitcnt lgkmcnt(4)
	v_mfma_f32_16x16x32_bf16 v[92:95], v[232:235], v[8:11], v[92:95]
	ds_read_b128 v[228:231], v255 offset:128
	s_waitcnt lgkmcnt(4)
	v_mfma_f32_16x16x32_bf16 v[96:99], v[236:239], v[4:7], v[176:179]
	ds_read_b128 v[232:235], v255 offset:192
	s_waitcnt lgkmcnt(4)
	v_mfma_f32_16x16x32_bf16 v[96:99], v[240:243], v[8:11], v[96:99]
	ds_read_b128 v[236:239], v255 offset:4736
	s_waitcnt lgkmcnt(4)
	v_mfma_f32_16x16x32_bf16 v[100:103], v[244:247], v[4:7], v[180:183]
	ds_read_b128 v[240:243], v255 offset:4800
	s_waitcnt lgkmcnt(4)
	v_mfma_f32_16x16x32_bf16 v[100:103], v[248:251], v[8:11], v[100:103]
	ds_read_b128 v[244:247], v255 offset:9344
	s_waitcnt lgkmcnt(4)
	v_mfma_f32_16x16x32_bf16 v[104:107], v[228:231], v[12:15], v[204:207]
	ds_read_b128 v[248:251], v255 offset:9408
	s_waitcnt lgkmcnt(4)
	v_mfma_f32_16x16x32_bf16 v[104:107], v[232:235], v[16:19], v[104:107]
	ds_read_b128 v[228:231], v255 offset:13952
	s_waitcnt lgkmcnt(4)
	v_mfma_f32_16x16x32_bf16 v[108:111], v[236:239], v[12:15], v[208:211]
	ds_read_b128 v[232:235], v255 offset:14016
	s_waitcnt lgkmcnt(4)
	v_mfma_f32_16x16x32_bf16 v[108:111], v[240:243], v[16:19], v[108:111]
	s_waitcnt lgkmcnt(3)
	v_mfma_f32_16x16x32_bf16 v[112:115], v[244:247], v[12:15], v[184:187]
	s_waitcnt lgkmcnt(2)
	v_mfma_f32_16x16x32_bf16 v[112:115], v[248:251], v[16:19], v[112:115]
	s_waitcnt lgkmcnt(1)
	v_mfma_f32_16x16x32_bf16 v[116:119], v[228:231], v[12:15], v[188:191]
	s_waitcnt lgkmcnt(0)
	v_mfma_f32_16x16x32_bf16 v[116:119], v[232:235], v[16:19], v[116:119]
	v_exp_f32_e32 v138, v88
	v_exp_f32_e32 v139, v89
	v_exp_f32_e32 v140, v90
	v_exp_f32_e32 v141, v91
	v_exp_f32_e32 v142, v92
	v_exp_f32_e32 v143, v93
	v_exp_f32_e32 v144, v94
	v_exp_f32_e32 v145, v95
	v_exp_f32_e32 v146, v96
	v_exp_f32_e32 v147, v97
	v_exp_f32_e32 v148, v98
	v_exp_f32_e32 v149, v99
	v_exp_f32_e32 v194, v100
	v_exp_f32_e32 v195, v101
	v_exp_f32_e32 v196, v102
	v_exp_f32_e32 v197, v103
	s_nop 0
	v_add_f32_e32 v26, v138, v139
	v_add_f32_e32 v26, v26, v140
	v_add_f32_e32 v26, v26, v141
	v_add_f32_e32 v26, v26, v142
	v_add_f32_e32 v26, v26, v143
	v_add_f32_e32 v26, v26, v144
	v_add_f32_e32 v26, v26, v145
	v_add_f32_e32 v26, v26, v146
	v_add_f32_e32 v26, v26, v147
	v_add_f32_e32 v26, v26, v148
	v_add_f32_e32 v26, v26, v149
	v_add_f32_e32 v26, v26, v194
	v_add_f32_e32 v26, v26, v195
	v_add_f32_e32 v26, v26, v196
	v_add_f32_e32 v26, v26, v197
	v_cmp_lt_f32_e32 vcc, s66, v26
	s_cbranch_vccnz .Ld_rare_A0_0

.Ld_back_A0_1:
	v_add_f32_e32 v151, v151, v26
	v_cvt_pk_bf16_f32 v128, v138, v139
	v_cvt_pk_bf16_f32 v129, v140, v141
	v_cvt_pk_bf16_f32 v130, v142, v143
	v_cvt_pk_bf16_f32 v131, v144, v145
	v_cvt_pk_bf16_f32 v152, v146, v147
	v_cvt_pk_bf16_f32 v153, v148, v149
	v_cvt_pk_bf16_f32 v154, v194, v195
	v_cvt_pk_bf16_f32 v155, v196, v197
	v_add_f32_e32 v165, 0x42800000, v165
	v_mov_b32_e32 v156, v165
	v_add_f32_e32 v157, 0x3f800000, v165
	v_add_f32_e32 v158, 0x40000000, v165
	v_add_f32_e32 v159, 0x40400000, v165
	v_add_f32_e32 v160, 0x41800000, v165
	v_add_f32_e32 v161, 0x41880000, v165
	v_add_f32_e32 v162, 0x41900000, v165
	v_add_f32_e32 v163, 0x41980000, v165
	v_add_f32_e32 v176, 0x42000000, v165
	v_add_f32_e32 v177, 0x42040000, v165
	v_add_f32_e32 v178, 0x42080000, v165
	v_add_f32_e32 v179, 0x420c0000, v165
	v_add_f32_e32 v180, 0x42400000, v165
	v_add_f32_e32 v181, 0x42440000, v165
	v_add_f32_e32 v182, 0x42480000, v165
	v_add_f32_e32 v183, 0x424c0000, v165
	v_fma_f32 v204, -v150, |v156|, v25
	v_fma_f32 v205, -v150, |v157|, v25
	v_fma_f32 v206, -v150, |v158|, v25
	v_fma_f32 v207, -v150, |v159|, v25
	v_fma_f32 v208, -v150, |v160|, v25
	v_fma_f32 v209, -v150, |v161|, v25
	v_fma_f32 v210, -v150, |v162|, v25
	v_fma_f32 v211, -v150, |v163|, v25
	v_fma_f32 v184, -v150, |v176|, v25
	v_fma_f32 v185, -v150, |v177|, v25
	v_fma_f32 v186, -v150, |v178|, v25
	v_fma_f32 v187, -v150, |v179|, v25
	v_fma_f32 v188, -v150, |v180|, v25
	v_fma_f32 v189, -v150, |v181|, v25
	v_fma_f32 v190, -v150, |v182|, v25
	v_fma_f32 v191, -v150, |v183|, v25
	v_fma_f32 v156, -v150, |v156|, v24
	v_fma_f32 v157, -v150, |v157|, v24
	v_fma_f32 v158, -v150, |v158|, v24
	v_fma_f32 v159, -v150, |v159|, v24
	v_fma_f32 v160, -v150, |v160|, v24
	v_fma_f32 v161, -v150, |v161|, v24
	v_fma_f32 v162, -v150, |v162|, v24
	v_fma_f32 v163, -v150, |v163|, v24
	v_fma_f32 v176, -v150, |v176|, v24
	v_fma_f32 v177, -v150, |v177|, v24
	v_fma_f32 v178, -v150, |v178|, v24
	v_fma_f32 v179, -v150, |v179|, v24
	v_fma_f32 v180, -v150, |v180|, v24
	v_fma_f32 v181, -v150, |v181|, v24
	v_fma_f32 v182, -v150, |v182|, v24
	v_fma_f32 v183, -v150, |v183|, v24
	s_waitcnt vmcnt(0)
	ds_write_b128 v169, v[212:215] offset:18432
	ds_write_b128 v169, v[216:219] offset:27648
	ds_write_b128 v164, v[220:223] offset:36864
	ds_write_b128 v164, v[224:227] offset:46080
	s_mov_b32 s31, s38
	s_mov_b32 s38, s39
	s_add_i32 s39, s39, 0x4800
	s_cmp_lg_u32 s39, 0xd800
	s_cselect_b32 s39, s39, 0
	s_mov_b32 s66, 0x5f800000
	s_mov_b32 s67, 0x42000000
	s_add_i32 s5, s5, 1
	s_min_u32 s8, s5, 62
	s_add_i32 s8, s8, 1
	s_mul_i32 s30, s8, 0xf8000
	v_add_u32_e32 v174, s31, v168
	v_add_u32_e32 v164, s39, v169
	s_add_u32 s80, s42, s30
	s_addc_u32 s81, s43, 0
	s_add_u32 s86, s80, 0x7c000
	s_addc_u32 s87, s81, 0
	s_add_u32 s96, s46, s30
	s_addc_u32 s97, s47, 0
	s_add_u32 s98, s96, 0x7c000
	s_addc_u32 s99, s97, 0
	s_waitcnt lgkmcnt(0)
	s_barrier
	global_load_dwordx4 v[212:215], v173, s[80:81]
	global_load_dwordx4 v[220:223], v175, s[96:97]
	global_load_dwordx4 v[216:219], v173, s[86:87]
	global_load_dwordx4 v[224:227], v175, s[98:99]
	ds_read_b64_tr_b16 v[228:229], v174 offset:36864
	ds_read_b64_tr_b16 v[230:231], v174 offset:41472
	ds_read_b64_tr_b16 v[232:233], v174 offset:36896
	ds_read_b64_tr_b16 v[234:235], v174 offset:41504
	ds_read_b64_tr_b16 v[236:237], v174 offset:36928
	ds_read_b64_tr_b16 v[238:239], v174 offset:41536
	ds_read_b64_tr_b16 v[240:241], v174 offset:36960
	ds_read_b64_tr_b16 v[242:243], v174 offset:41568
	ds_read_b64_tr_b16 v[244:245], v174 offset:36992
	ds_read_b64_tr_b16 v[246:247], v174 offset:41600
	s_waitcnt lgkmcnt(8)
	v_mfma_f32_16x16x32_bf16 v[28:31], v[228:231], v[120:123], v[28:31]
	v_mfma_f32_16x16x32_bf16 v[36:39], v[228:231], v[128:131], v[36:39]
	ds_read_b64_tr_b16 v[248:249], v174 offset:37024
	ds_read_b64_tr_b16 v[250:251], v174 offset:41632
	s_waitcnt lgkmcnt(8)
	v_mfma_f32_16x16x32_bf16 v[32:35], v[232:235], v[120:123], v[32:35]
	v_mfma_f32_16x16x32_bf16 v[44:47], v[232:235], v[128:131], v[44:47]
	ds_read_b64_tr_b16 v[228:229], v174 offset:37056
	ds_read_b64_tr_b16 v[230:231], v174 offset:41664
	s_waitcnt lgkmcnt(8)
	v_mfma_f32_16x16x32_bf16 v[40:43], v[236:239], v[120:123], v[40:43]
	v_mfma_f32_16x16x32_bf16 v[48:51], v[236:239], v[128:131], v[48:51]
	ds_read_b64_tr_b16 v[232:233], v174 offset:37088
	ds_read_b64_tr_b16 v[234:235], v174 offset:41696
	s_waitcnt lgkmcnt(8)
	v_mfma_f32_16x16x32_bf16 v[52:55], v[240:243], v[120:123], v[52:55]
	v_mfma_f32_16x16x32_bf16 v[60:63], v[240:243], v[128:131], v[60:63]
	ds_read_b64_tr_b16 v[236:237], v174 offset:46080
	ds_read_b64_tr_b16 v[238:239], v174 offset:50688
	s_waitcnt lgkmcnt(8)
	v_mfma_f32_16x16x32_bf16 v[56:59], v[244:247], v[120:123], v[56:59]
	v_mfma_f32_16x16x32_bf16 v[68:71], v[244:247], v[128:131], v[68:71]
	ds_read_b64_tr_b16 v[240:241], v174 offset:46112
	ds_read_b64_tr_b16 v[242:243], v174 offset:50720
	s_waitcnt lgkmcnt(8)
	v_mfma_f32_16x16x32_bf16 v[64:67], v[248:251], v[120:123], v[64:67]
	v_mfma_f32_16x16x32_bf16 v[76:79], v[248:251], v[128:131], v[76:79]
	ds_read_b64_tr_b16 v[244:245], v174 offset:46144
	ds_read_b64_tr_b16 v[246:247], v174 offset:50752
	s_waitcnt lgkmcnt(8)
	v_mfma_f32_16x16x32_bf16 v[72:75], v[228:231], v[120:123], v[72:75]
	v_mfma_f32_16x16x32_bf16 v[80:83], v[228:231], v[128:131], v[80:83]
	ds_read_b64_tr_b16 v[248:249], v174 offset:46176
	ds_read_b64_tr_b16 v[250:251], v174 offset:50784
	s_waitcnt lgkmcnt(8)
	v_mfma_f32_16x16x32_bf16 v[84:87], v[232:235], v[120:123], v[84:87]
	v_mfma_f32_16x16x32_bf16 v[20:23], v[232:235], v[128:131], v[20:23]
	ds_read_b64_tr_b16 v[228:229], v174 offset:46208
	ds_read_b64_tr_b16 v[230:231], v174 offset:50816
	s_waitcnt lgkmcnt(8)
	v_mfma_f32_16x16x32_bf16 v[28:31], v[236:239], v[124:127], v[28:31]
	v_mfma_f32_16x16x32_bf16 v[36:39], v[236:239], v[152:155], v[36:39]
	ds_read_b64_tr_b16 v[232:233], v174 offset:46240
	ds_read_b64_tr_b16 v[234:235], v174 offset:50848
	s_waitcnt lgkmcnt(8)
	v_mfma_f32_16x16x32_bf16 v[32:35], v[240:243], v[124:127], v[32:35]
	v_mfma_f32_16x16x32_bf16 v[44:47], v[240:243], v[152:155], v[44:47]
	ds_read_b64_tr_b16 v[236:237], v174 offset:46272
	ds_read_b64_tr_b16 v[238:239], v174 offset:50880
	s_waitcnt lgkmcnt(8)
	v_mfma_f32_16x16x32_bf16 v[40:43], v[244:247], v[124:127], v[40:43]
	v_mfma_f32_16x16x32_bf16 v[48:51], v[244:247], v[152:155], v[48:51]
	ds_read_b64_tr_b16 v[240:241], v174 offset:46304
	ds_read_b64_tr_b16 v[242:243], v174 offset:50912
	s_waitcnt lgkmcnt(8)
	v_mfma_f32_16x16x32_bf16 v[52:55], v[248:251], v[124:127], v[52:55]
	v_mfma_f32_16x16x32_bf16 v[60:63], v[248:251], v[152:155], v[60:63]
	ds_read_b128 v[244:247], v255 offset:18432
	s_waitcnt lgkmcnt(7)
	v_mfma_f32_16x16x32_bf16 v[56:59], v[228:231], v[124:127], v[56:59]
	v_mfma_f32_16x16x32_bf16 v[68:71], v[228:231], v[152:155], v[68:71]
	ds_read_b128 v[248:251], v255 offset:18496
	s_waitcnt lgkmcnt(6)
	v_mfma_f32_16x16x32_bf16 v[64:67], v[232:235], v[124:127], v[64:67]
	v_mfma_f32_16x16x32_bf16 v[76:79], v[232:235], v[152:155], v[76:79]
	ds_read_b128 v[228:231], v255 offset:23040
	s_waitcnt lgkmcnt(5)
	v_mfma_f32_16x16x32_bf16 v[72:75], v[236:239], v[124:127], v[72:75]
	v_mfma_f32_16x16x32_bf16 v[80:83], v[236:239], v[152:155], v[80:83]
	ds_read_b128 v[232:235], v255 offset:23104
	s_waitcnt lgkmcnt(4)
	v_mfma_f32_16x16x32_bf16 v[84:87], v[240:243], v[124:127], v[84:87]
	v_mfma_f32_16x16x32_bf16 v[20:23], v[240:243], v[152:155], v[20:23]
	ds_read_b128 v[236:239], v255 offset:27648
	s_waitcnt lgkmcnt(4)
	v_mfma_f32_16x16x32_bf16 v[88:91], v[244:247], v[4:7], v[156:159]
	ds_read_b128 v[240:243], v255 offset:27712
	s_waitcnt lgkmcnt(4)
	v_mfma_f32_16x16x32_bf16 v[88:91], v[248:251], v[8:11], v[88:91]
	ds_read_b128 v[244:247], v255 offset:32256
	s_waitcnt lgkmcnt(4)
	v_mfma_f32_16x16x32_bf16 v[92:95], v[228:231], v[4:7], v[160:163]
	ds_read_b128 v[248:251], v255 offset:32320
	s_waitcnt lgkmcnt(4)
	v_mfma_f32_16x16x32_bf16 v[92:95], v[232:235], v[8:11], v[92:95]
	ds_read_b128 v[228:231], v255 offset:18560
	s_waitcnt lgkmcnt(4)
	v_mfma_f32_16x16x32_bf16 v[96:99], v[236:239], v[4:7], v[176:179]
	ds_read_b128 v[232:235], v255 offset:18624
	s_waitcnt lgkmcnt(4)
	v_mfma_f32_16x16x32_bf16 v[96:99], v[240:243], v[8:11], v[96:99]
	ds_read_b128 v[236:239], v255 offset:23168
	s_waitcnt lgkmcnt(4)
	v_mfma_f32_16x16x32_bf16 v[100:103], v[244:247], v[4:7], v[180:183]
	ds_read_b128 v[240:243], v255 offset:23232
	s_waitcnt lgkmcnt(4)
	v_mfma_f32_16x16x32_bf16 v[100:103], v[248:251], v[8:11], v[100:103]
	ds_read_b128 v[244:247], v255 offset:27776
	s_waitcnt lgkmcnt(4)
	v_mfma_f32_16x16x32_bf16 v[104:107], v[228:231], v[12:15], v[204:207]
	ds_read_b128 v[248:251], v255 offset:27840
	s_waitcnt lgkmcnt(4)
	v_mfma_f32_16x16x32_bf16 v[104:107], v[232:235], v[16:19], v[104:107]
	ds_read_b128 v[228:231], v255 offset:32384
	s_waitcnt lgkmcnt(4)
	v_mfma_f32_16x16x32_bf16 v[108:111], v[236:239], v[12:15], v[208:211]
	ds_read_b128 v[232:235], v255 offset:32448
	s_waitcnt lgkmcnt(4)
	v_mfma_f32_16x16x32_bf16 v[108:111], v[240:243], v[16:19], v[108:111]
	s_waitcnt lgkmcnt(3)
	v_mfma_f32_16x16x32_bf16 v[112:115], v[244:247], v[12:15], v[184:187]
	s_waitcnt lgkmcnt(2)
	v_mfma_f32_16x16x32_bf16 v[112:115], v[248:251], v[16:19], v[112:115]
	s_waitcnt lgkmcnt(1)
	v_mfma_f32_16x16x32_bf16 v[116:119], v[228:231], v[12:15], v[188:191]
	s_waitcnt lgkmcnt(0)
	v_mfma_f32_16x16x32_bf16 v[116:119], v[232:235], v[16:19], v[116:119]
	v_exp_f32_e32 v138, v88
	v_exp_f32_e32 v139, v89
	v_exp_f32_e32 v140, v90
	v_exp_f32_e32 v141, v91
	v_exp_f32_e32 v142, v92
	v_exp_f32_e32 v143, v93
	v_exp_f32_e32 v144, v94
	v_exp_f32_e32 v145, v95
	v_exp_f32_e32 v146, v96
	v_exp_f32_e32 v147, v97
	v_exp_f32_e32 v148, v98
	v_exp_f32_e32 v149, v99
	v_exp_f32_e32 v194, v100
	v_exp_f32_e32 v195, v101
	v_exp_f32_e32 v196, v102
	v_exp_f32_e32 v197, v103
	s_nop 0
	v_add_f32_e32 v26, v138, v139
	v_add_f32_e32 v26, v26, v140
	v_add_f32_e32 v26, v26, v141
	v_add_f32_e32 v26, v26, v142
	v_add_f32_e32 v26, v26, v143
	v_add_f32_e32 v26, v26, v144
	v_add_f32_e32 v26, v26, v145
	v_add_f32_e32 v26, v26, v146
	v_add_f32_e32 v26, v26, v147
	v_add_f32_e32 v26, v26, v148
	v_add_f32_e32 v26, v26, v149
	v_add_f32_e32 v26, v26, v194
	v_add_f32_e32 v26, v26, v195
	v_add_f32_e32 v26, v26, v196
	v_add_f32_e32 v26, v26, v197
	v_cmp_lt_f32_e32 vcc, s66, v26
	s_cbranch_vccnz .Ld_rare_A1_0

.Ld_back_A1_1:
	v_add_f32_e32 v151, v151, v26
	v_cvt_pk_bf16_f32 v128, v138, v139
	v_cvt_pk_bf16_f32 v129, v140, v141
	v_cvt_pk_bf16_f32 v130, v142, v143
	v_cvt_pk_bf16_f32 v131, v144, v145
	v_cvt_pk_bf16_f32 v152, v146, v147
	v_cvt_pk_bf16_f32 v153, v148, v149
	v_cvt_pk_bf16_f32 v154, v194, v195
	v_cvt_pk_bf16_f32 v155, v196, v197
	v_add_f32_e32 v165, 0x42800000, v165
	v_mov_b32_e32 v156, v165
	v_add_f32_e32 v157, 0x3f800000, v165
	v_add_f32_e32 v158, 0x40000000, v165
	v_add_f32_e32 v159, 0x40400000, v165
	v_add_f32_e32 v160, 0x41800000, v165
	v_add_f32_e32 v161, 0x41880000, v165
	v_add_f32_e32 v162, 0x41900000, v165
	v_add_f32_e32 v163, 0x41980000, v165
	v_add_f32_e32 v176, 0x42000000, v165
	v_add_f32_e32 v177, 0x42040000, v165
	v_add_f32_e32 v178, 0x42080000, v165
	v_add_f32_e32 v179, 0x420c0000, v165
	v_add_f32_e32 v180, 0x42400000, v165
	v_add_f32_e32 v181, 0x42440000, v165
	v_add_f32_e32 v182, 0x42480000, v165
	v_add_f32_e32 v183, 0x424c0000, v165
	v_fma_f32 v204, -v150, |v156|, v25
	v_fma_f32 v205, -v150, |v157|, v25
	v_fma_f32 v206, -v150, |v158|, v25
	v_fma_f32 v207, -v150, |v159|, v25
	v_fma_f32 v208, -v150, |v160|, v25
	v_fma_f32 v209, -v150, |v161|, v25
	v_fma_f32 v210, -v150, |v162|, v25
	v_fma_f32 v211, -v150, |v163|, v25
	v_fma_f32 v184, -v150, |v176|, v25
	v_fma_f32 v185, -v150, |v177|, v25
	v_fma_f32 v186, -v150, |v178|, v25
	v_fma_f32 v187, -v150, |v179|, v25
	v_fma_f32 v188, -v150, |v180|, v25
	v_fma_f32 v189, -v150, |v181|, v25
	v_fma_f32 v190, -v150, |v182|, v25
	v_fma_f32 v191, -v150, |v183|, v25
	v_fma_f32 v156, -v150, |v156|, v24
	v_fma_f32 v157, -v150, |v157|, v24
	v_fma_f32 v158, -v150, |v158|, v24
	v_fma_f32 v159, -v150, |v159|, v24
	v_fma_f32 v160, -v150, |v160|, v24
	v_fma_f32 v161, -v150, |v161|, v24
	v_fma_f32 v162, -v150, |v162|, v24
	v_fma_f32 v163, -v150, |v163|, v24
	v_fma_f32 v176, -v150, |v176|, v24
	v_fma_f32 v177, -v150, |v177|, v24
	v_fma_f32 v178, -v150, |v178|, v24
	v_fma_f32 v179, -v150, |v179|, v24
	v_fma_f32 v180, -v150, |v180|, v24
	v_fma_f32 v181, -v150, |v181|, v24
	v_fma_f32 v182, -v150, |v182|, v24
	v_fma_f32 v183, -v150, |v183|, v24
	s_waitcnt vmcnt(0)
	ds_write_b128 v169, v[212:215] offset:0
	ds_write_b128 v169, v[216:219] offset:9216
	ds_write_b128 v164, v[220:223] offset:36864
	ds_write_b128 v164, v[224:227] offset:46080
	s_mov_b32 s31, s38
	s_mov_b32 s38, s39
	s_add_i32 s39, s39, 0x4800
	s_cmp_lg_u32 s39, 0xd800
	s_cselect_b32 s39, s39, 0
	s_mov_b32 s66, 0x5f800000
	s_mov_b32 s67, 0x42000000
	s_add_i32 s5, s5, 1
	s_min_u32 s8, s5, 62
	s_add_i32 s8, s8, 1
	s_mul_i32 s30, s8, 0xf8000
	v_add_u32_e32 v174, s31, v168
	v_add_u32_e32 v164, s39, v169
	s_add_u32 s80, s42, s30
	s_addc_u32 s81, s43, 0
	s_add_u32 s86, s80, 0x7c000
	s_addc_u32 s87, s81, 0
	s_add_u32 s96, s46, s30
	s_addc_u32 s97, s47, 0
	s_add_u32 s98, s96, 0x7c000
	s_addc_u32 s99, s97, 0
	s_waitcnt lgkmcnt(0)
	s_barrier
	s_cmp_lt_u32 s5, 64
	s_cbranch_scc1 .Ld_loopA
	v_add_u32_e32 v174, s31, v168
	ds_read_b64_tr_b16 v[228:229], v174 offset:36864
	ds_read_b64_tr_b16 v[230:231], v174 offset:41472
	ds_read_b64_tr_b16 v[232:233], v174 offset:36896
	ds_read_b64_tr_b16 v[234:235], v174 offset:41504
	ds_read_b64_tr_b16 v[236:237], v174 offset:36928
	ds_read_b64_tr_b16 v[238:239], v174 offset:41536
	ds_read_b64_tr_b16 v[240:241], v174 offset:36960
	ds_read_b64_tr_b16 v[242:243], v174 offset:41568
	ds_read_b64_tr_b16 v[244:245], v174 offset:36992
	ds_read_b64_tr_b16 v[246:247], v174 offset:41600
	s_waitcnt lgkmcnt(8)
	v_mfma_f32_16x16x32_bf16 v[28:31], v[228:231], v[120:123], v[28:31]
	v_mfma_f32_16x16x32_bf16 v[36:39], v[228:231], v[128:131], v[36:39]
	ds_read_b64_tr_b16 v[248:249], v174 offset:37024
	ds_read_b64_tr_b16 v[250:251], v174 offset:41632
	s_waitcnt lgkmcnt(8)
	v_mfma_f32_16x16x32_bf16 v[32:35], v[232:235], v[120:123], v[32:35]
	v_mfma_f32_16x16x32_bf16 v[44:47], v[232:235], v[128:131], v[44:47]
	ds_read_b64_tr_b16 v[228:229], v174 offset:37056
	ds_read_b64_tr_b16 v[230:231], v174 offset:41664
	s_waitcnt lgkmcnt(8)
	v_mfma_f32_16x16x32_bf16 v[40:43], v[236:239], v[120:123], v[40:43]
	v_mfma_f32_16x16x32_bf16 v[48:51], v[236:239], v[128:131], v[48:51]
	ds_read_b64_tr_b16 v[232:233], v174 offset:37088
	ds_read_b64_tr_b16 v[234:235], v174 offset:41696
	s_waitcnt lgkmcnt(8)
	v_mfma_f32_16x16x32_bf16 v[52:55], v[240:243], v[120:123], v[52:55]
	v_mfma_f32_16x16x32_bf16 v[60:63], v[240:243], v[128:131], v[60:63]
	ds_read_b64_tr_b16 v[236:237], v174 offset:46080
	ds_read_b64_tr_b16 v[238:239], v174 offset:50688
	s_waitcnt lgkmcnt(8)
	v_mfma_f32_16x16x32_bf16 v[56:59], v[244:247], v[120:123], v[56:59]
	v_mfma_f32_16x16x32_bf16 v[68:71], v[244:247], v[128:131], v[68:71]
	ds_read_b64_tr_b16 v[240:241], v174 offset:46112
	ds_read_b64_tr_b16 v[242:243], v174 offset:50720
	s_waitcnt lgkmcnt(8)
	v_mfma_f32_16x16x32_bf16 v[64:67], v[248:251], v[120:123], v[64:67]
	v_mfma_f32_16x16x32_bf16 v[76:79], v[248:251], v[128:131], v[76:79]
	ds_read_b64_tr_b16 v[244:245], v174 offset:46144
	ds_read_b64_tr_b16 v[246:247], v174 offset:50752
	s_waitcnt lgkmcnt(8)
	v_mfma_f32_16x16x32_bf16 v[72:75], v[228:231], v[120:123], v[72:75]
	v_mfma_f32_16x16x32_bf16 v[80:83], v[228:231], v[128:131], v[80:83]
	ds_read_b64_tr_b16 v[248:249], v174 offset:46176
	ds_read_b64_tr_b16 v[250:251], v174 offset:50784
	s_waitcnt lgkmcnt(8)
	v_mfma_f32_16x16x32_bf16 v[84:87], v[232:235], v[120:123], v[84:87]
	v_mfma_f32_16x16x32_bf16 v[20:23], v[232:235], v[128:131], v[20:23]
	ds_read_b64_tr_b16 v[228:229], v174 offset:46208
	ds_read_b64_tr_b16 v[230:231], v174 offset:50816
	s_waitcnt lgkmcnt(8)
	v_mfma_f32_16x16x32_bf16 v[28:31], v[236:239], v[124:127], v[28:31]
	v_mfma_f32_16x16x32_bf16 v[36:39], v[236:239], v[152:155], v[36:39]
	ds_read_b64_tr_b16 v[232:233], v174 offset:46240
	ds_read_b64_tr_b16 v[234:235], v174 offset:50848
	s_waitcnt lgkmcnt(8)
	v_mfma_f32_16x16x32_bf16 v[32:35], v[240:243], v[124:127], v[32:35]
	v_mfma_f32_16x16x32_bf16 v[44:47], v[240:243], v[152:155], v[44:47]
	ds_read_b64_tr_b16 v[236:237], v174 offset:46272
	ds_read_b64_tr_b16 v[238:239], v174 offset:50880
	s_waitcnt lgkmcnt(8)
	v_mfma_f32_16x16x32_bf16 v[40:43], v[244:247], v[124:127], v[40:43]
	v_mfma_f32_16x16x32_bf16 v[48:51], v[244:247], v[152:155], v[48:51]
	ds_read_b64_tr_b16 v[240:241], v174 offset:46304
	ds_read_b64_tr_b16 v[242:243], v174 offset:50912
	s_waitcnt lgkmcnt(8)
	v_mfma_f32_16x16x32_bf16 v[52:55], v[248:251], v[124:127], v[52:55]
	v_mfma_f32_16x16x32_bf16 v[60:63], v[248:251], v[152:155], v[60:63]
	s_waitcnt lgkmcnt(6)
	v_mfma_f32_16x16x32_bf16 v[56:59], v[228:231], v[124:127], v[56:59]
	v_mfma_f32_16x16x32_bf16 v[68:71], v[228:231], v[152:155], v[68:71]
	s_waitcnt lgkmcnt(4)
	v_mfma_f32_16x16x32_bf16 v[64:67], v[232:235], v[124:127], v[64:67]
	v_mfma_f32_16x16x32_bf16 v[76:79], v[232:235], v[152:155], v[76:79]
	s_waitcnt lgkmcnt(2)
	v_mfma_f32_16x16x32_bf16 v[72:75], v[236:239], v[124:127], v[72:75]
	v_mfma_f32_16x16x32_bf16 v[80:83], v[236:239], v[152:155], v[80:83]
	s_waitcnt lgkmcnt(0)
	v_mfma_f32_16x16x32_bf16 v[84:87], v[240:243], v[124:127], v[84:87]
	v_mfma_f32_16x16x32_bf16 v[20:23], v[240:243], v[152:155], v[20:23]
	v_mov_b32_e32 v138, 0xa00
	v_mov_b32_e32 v139, 0x0
	v_mov_b32_e32 v140, 0x9ff
	v_mov_b32_e32 v141, 0x0
	v_mov_b32_e32 v142, 0x200
	v_mov_b32_e32 v143, 0x0
	v_mov_b32_e32 v144, 0x1ff
	v_mov_b32_e32 v145, 0x0
	v_mov_b32_e32 v146, 0xb00
	v_mov_b32_e32 v147, 0x0
	v_mov_b32_e32 v148, 0xaff
	v_mov_b32_e32 v149, 0x0
	v_mov_b32_e32 v194, 0x358637bd
	v_mov_b32_e32 v195, 0x2000
	v_mov_b32_e32 v196, 0x3e38aa3b
	v_mov_b32_e32 v197, 0x41b17218
